# weight-conversion split: late-use matrices converted by idle CUs during mix-in GEMM tail round; g-gain loads hoisted
# speedup vs baseline: 1.0128x; 1.0128x over previous
.LBB0_10:
	s_movk_i32 s0, 0x1400
	v_writelane_b32 v247, s0, 0
	s_mov_b32 s0, 0
	s_nop 1
	v_writelane_b32 v247, s0, 1
	s_nop 1
	v_writelane_b32 v247, s0, 3
	s_nop 1
	v_writelane_b32 v247, s0, 6
	s_movk_i32 s0, 0xb00
	s_nop 0
	v_writelane_b32 v247, s0, 2
	s_movk_i32 s0, 0x2800
	s_nop 0
	v_writelane_b32 v247, s0, 5
	s_waitcnt lgkmcnt(0)
	s_lshl_b32 s0, s66, 3
	s_nop 0
	v_writelane_b32 v247, s0, 4
	s_lshr_b32 s100, s2, 6
	s_lshl_b32 s0, s74, 3
	s_add_i32 s100, s100, s0

.LBB0_13:
	v_readlane_b32 s4, v247, 4
	v_readlane_b32 s5, v247, 5
	s_nop 0
	s_add_i32 s100, s100, s4
	s_cmp_lt_i32 s100, s5
	s_cbranch_scc0 .LBB0_129
.LBB0_14:
	v_readlane_b32 s2, v247, 0
	v_readlane_b32 s4, v247, 1
	v_readlane_b32 s5, v247, 2
	v_readlane_b32 s42, v247, 3
	s_nop 0
	s_cmp_ge_i32 s100, s2
	s_cselect_b32 s43, 1, 0
	s_cselect_b32 s2, s2, 0
	s_sub_i32 s2, s100, s2
	s_cmpk_lt_i32 s2, 0xb00
	s_cselect_b32 s4, s4, s5
	s_add_i32 s2, s2, s4
	s_add_i32 s42, s42, s43
	s_mulk_i32 s42, 0x2680
	s_add_i32 s69, s2, s42
	s_lshl_b32 s46, s69, 7
	s_mul_hi_i32 s2, s69, 0x3531dec1
	s_lshr_b32 s4, s2, 31
	s_ashr_i32 s2, s2, 11
	s_add_i32 s42, s2, s4
	s_mul_i32 s2, s42, 0xffffd980
	s_add_i32 s70, s69, s2
	s_ashr_i32 s43, s42, 31
	s_mul_i32 s4, s42, 0x9a00000
	s_mul_hi_i32 s2, s42, 0x9a00000
	s_add_u32 s40, s3, s4
	s_addc_u32 s41, s33, s2
	s_cmpk_gt_i32 s70, 0xaff
	s_mov_b64 s[4:5], -1
	s_cbranch_scc0 .LBB0_96
	s_cmpk_gt_u32 s70, 0x15ff
	s_cbranch_scc0 .LBB0_61
	s_cmpk_gt_u32 s70, 0x197f
	s_cbranch_scc0 .LBB0_26
	s_cmpk_gt_u32 s70, 0x1eff
	s_cbranch_scc0 .LBB0_23
	s_and_b32 s44, s46, 0x780
	s_cmpk_gt_u32 s70, 0x247f
	s_cbranch_scc0 .LBB0_20
	s_lshl_b64 s[4:5], s[42:43], 24
	s_add_u32 s4, s16, s4
	s_addc_u32 s5, s17, s5
	s_add_i32 s2, s70, 0xdb80
	s_bfe_u32 s2, s2, 0xc0004
	v_lshlrev_b32_e32 v2, 2, v135
	v_lshl_or_b32 v132, s2, 19, v2
	v_lshl_add_u64 v[2:3], s[4:5], 0, v[132:133]
	s_lshl_b32 s38, s44, 2
	v_lshl_add_u64 v[2:3], v[2:3], 0, s[38:39]
	v_lshlrev_b32_e32 v132, 2, v130
	v_lshl_add_u64 v[2:3], v[2:3], 0, v[132:133]
	v_add_co_u32_e32 v4, vcc, s68, v2
	s_mov_b32 s4, 0x8000
	s_nop 0
	v_addc_co_u32_e32 v5, vcc, 0, v3, vcc
	global_load_dwordx4 v[106:109], v[2:3], off
	global_load_dwordx4 v[110:113], v[4:5], off
	v_add_co_u32_e32 v4, vcc, s4, v2
	s_mov_b32 s4, 0xa000
	s_nop 0
	v_addc_co_u32_e32 v5, vcc, 0, v3, vcc
	v_add_co_u32_e32 v6, vcc, s4, v2
	s_mov_b32 s4, 0x10000
	s_nop 0
	v_addc_co_u32_e32 v7, vcc, 0, v3, vcc
	global_load_dwordx4 v[114:117], v[4:5], off
	global_load_dwordx4 v[118:121], v[6:7], off
	v_add_co_u32_e32 v4, vcc, s4, v2
	s_mov_b32 s4, 0x12000
	s_nop 0
	v_addc_co_u32_e32 v5, vcc, 0, v3, vcc
	v_add_co_u32_e32 v6, vcc, s4, v2
	s_mov_b32 s4, 0x18000
	s_nop 0
	v_addc_co_u32_e32 v7, vcc, 0, v3, vcc
	global_load_dwordx4 v[122:125], v[4:5], off
	global_load_dwordx4 v[126:129], v[6:7], off
	v_add_co_u32_e32 v4, vcc, s4, v2
	s_mov_b32 s4, 0x1a000
	s_nop 0
	v_addc_co_u32_e32 v5, vcc, 0, v3, vcc
	v_add_co_u32_e32 v6, vcc, s4, v2
	s_mov_b32 s4, 0x20000
	s_nop 0
	v_addc_co_u32_e32 v7, vcc, 0, v3, vcc
	global_load_dwordx4 v[98:101], v[4:5], off
	global_load_dwordx4 v[102:105], v[6:7], off
	v_add_co_u32_e32 v4, vcc, s4, v2
	s_mov_b32 s4, 0x22000
	s_nop 0
	v_addc_co_u32_e32 v5, vcc, 0, v3, vcc
	v_add_co_u32_e32 v6, vcc, s4, v2
	s_mov_b32 s4, 0x28000
	s_nop 0
	v_addc_co_u32_e32 v7, vcc, 0, v3, vcc
	global_load_dwordx4 v[90:93], v[4:5], off
	global_load_dwordx4 v[94:97], v[6:7], off
	v_add_co_u32_e32 v4, vcc, s4, v2
	s_mov_b32 s4, 0x30000
	s_nop 0
	v_addc_co_u32_e32 v5, vcc, 0, v3, vcc
	v_add_co_u32_e32 v6, vcc, s58, v2
	s_lshl_b32 s2, s2, 11
	s_nop 0
	v_addc_co_u32_e32 v7, vcc, 0, v3, vcc
	global_load_dwordx4 v[82:85], v[4:5], off
	global_load_dwordx4 v[86:89], v[6:7], off
	v_add_co_u32_e32 v4, vcc, s4, v2
	s_mov_b32 s4, 0x32000
	s_nop 0
	v_addc_co_u32_e32 v5, vcc, 0, v3, vcc
	v_add_co_u32_e32 v6, vcc, s4, v2
	s_mov_b32 s4, 0x3a000
	s_nop 0
	v_addc_co_u32_e32 v7, vcc, 0, v3, vcc
	global_load_dwordx4 v[74:77], v[4:5], off
	global_load_dwordx4 v[78:81], v[6:7], off
	v_add_co_u32_e32 v4, vcc, s61, v2
	s_waitcnt vmcnt(13)
	v_bfe_u32 v132, v106, 17, 1
	v_addc_co_u32_e32 v5, vcc, 0, v3, vcc
	v_add_co_u32_e32 v6, vcc, s4, v2
	s_mov_b32 s4, 0x40000
	s_nop 0
	v_addc_co_u32_e32 v7, vcc, 0, v3, vcc
	global_load_dwordx4 v[66:69], v[4:5], off
	global_load_dwordx4 v[70:73], v[6:7], off
	v_add_co_u32_e32 v4, vcc, s4, v2
	s_mov_b32 s4, 0x42000
	s_nop 0
	v_addc_co_u32_e32 v5, vcc, 0, v3, vcc
	v_add_co_u32_e32 v6, vcc, s4, v2
	s_mov_b32 s4, 0x48000
	s_nop 0
	v_addc_co_u32_e32 v7, vcc, 0, v3, vcc
	global_load_dwordx4 v[58:61], v[4:5], off
	global_load_dwordx4 v[62:65], v[6:7], off
	v_add_co_u32_e32 v4, vcc, s4, v2
	s_mov_b32 s4, 0x4a000
	s_nop 0
	v_addc_co_u32_e32 v5, vcc, 0, v3, vcc
	v_add_co_u32_e32 v6, vcc, s4, v2
	s_mov_b32 s4, 0x50000
	s_nop 0
	v_addc_co_u32_e32 v7, vcc, 0, v3, vcc
	global_load_dwordx4 v[50:53], v[4:5], off
	global_load_dwordx4 v[54:57], v[6:7], off
	v_add_co_u32_e32 v4, vcc, s4, v2
	v_add3_u32 v106, v106, v132, s86
	s_nop 0
	v_addc_co_u32_e32 v5, vcc, 0, v3, vcc
	v_add_co_u32_e32 v6, vcc, s75, v2
	s_waitcnt vmcnt(18)
	v_bfe_u32 v132, v110, 17, 1
	v_addc_co_u32_e32 v7, vcc, 0, v3, vcc
	global_load_dwordx4 v[42:45], v[4:5], off
	global_load_dwordx4 v[46:49], v[6:7], off
	v_add_co_u32_e32 v4, vcc, s76, v2
	v_add3_u32 v110, v110, v132, s86
	s_nop 0
	v_addc_co_u32_e32 v5, vcc, 0, v3, vcc
	v_add_co_u32_e32 v6, vcc, s77, v2
	v_and_b32_e32 v106, 0xfffe0000, v106
	s_nop 0
	v_addc_co_u32_e32 v7, vcc, 0, v3, vcc
	global_load_dwordx4 v[34:37], v[4:5], off
	global_load_dwordx4 v[38:41], v[6:7], off
	v_add_co_u32_e32 v4, vcc, s78, v2
	v_and_b32_e32 v110, 0xfffe0000, v110
	s_nop 0
	v_addc_co_u32_e32 v5, vcc, 0, v3, vcc
	v_add_co_u32_e32 v6, vcc, s79, v2
	v_lshlrev_b32_e32 v132, 1, v134
	s_nop 0
	v_addc_co_u32_e32 v7, vcc, 0, v3, vcc
	global_load_dwordx4 v[26:29], v[4:5], off
	global_load_dwordx4 v[30:33], v[6:7], off
	v_add_co_u32_e32 v4, vcc, s80, v2
	s_mov_b64 s[4:5], 0x5000000
	s_nop 0
	v_addc_co_u32_e32 v5, vcc, 0, v3, vcc
	v_add_co_u32_e32 v6, vcc, s81, v2
	s_nop 1
	v_addc_co_u32_e32 v7, vcc, 0, v3, vcc
	global_load_dwordx4 v[18:21], v[4:5], off
	global_load_dwordx4 v[22:25], v[6:7], off
	v_add_co_u32_e32 v4, vcc, s82, v2
	s_nop 1
	v_addc_co_u32_e32 v5, vcc, 0, v3, vcc
	v_add_co_u32_e32 v6, vcc, s83, v2
	s_nop 1
	v_addc_co_u32_e32 v7, vcc, 0, v3, vcc
	global_load_dwordx4 v[10:13], v[4:5], off
	global_load_dwordx4 v[14:17], v[6:7], off
	v_add_co_u32_e32 v4, vcc, s84, v2
	s_nop 1
	v_addc_co_u32_e32 v5, vcc, 0, v3, vcc
	v_add_co_u32_e32 v6, vcc, s85, v2
	s_nop 1
	v_addc_co_u32_e32 v7, vcc, 0, v3, vcc
	global_load_dwordx4 v[2:5], v[4:5], off
	s_nop 0
	global_load_dwordx4 v[6:9], v[6:7], off
	v_cvt_pk_bf16_f32 v106, v106, v110
	v_add_u32_e32 v110, v142, v143
	ds_write_b32 v110, v106
	v_bfe_u32 v106, v107, 17, 1
	v_add3_u32 v106, v107, v106, s86
	v_bfe_u32 v107, v111, 17, 1
	v_and_b32_e32 v106, 0xfffe0000, v106
	v_add3_u32 v107, v111, v107, s86
	v_and_b32_e32 v107, 0xfffe0000, v107
	v_cvt_pk_bf16_f32 v106, v106, v107
	ds_write_b32 v110, v106 offset:128
	v_bfe_u32 v106, v108, 17, 1
	v_add3_u32 v106, v108, v106, s86
	v_bfe_u32 v107, v112, 17, 1
	v_and_b32_e32 v106, 0xfffe0000, v106
	v_add3_u32 v107, v112, v107, s86
	v_and_b32_e32 v107, 0xfffe0000, v107
	v_cvt_pk_bf16_f32 v106, v106, v107
	ds_write_b32 v110, v106 offset:256
	v_bfe_u32 v106, v109, 17, 1
	v_add3_u32 v106, v109, v106, s86
	v_bfe_u32 v107, v113, 17, 1
	v_and_b32_e32 v106, 0xfffe0000, v106
	v_add3_u32 v107, v113, v107, s86
	v_and_b32_e32 v107, 0xfffe0000, v107
	v_cvt_pk_bf16_f32 v106, v106, v107
	ds_write_b32 v110, v106 offset:384
	s_waitcnt vmcnt(29)
	v_bfe_u32 v106, v114, 17, 1
	v_add3_u32 v106, v114, v106, s86
	s_waitcnt vmcnt(28)
	v_bfe_u32 v107, v118, 17, 1
	v_and_b32_e32 v106, 0xfffe0000, v106
	v_add3_u32 v107, v118, v107, s86
	v_and_b32_e32 v107, 0xfffe0000, v107
	v_cvt_pk_bf16_f32 v106, v106, v107
	ds_write_b32 v110, v106 offset:1032
	v_bfe_u32 v106, v115, 17, 1
	v_add3_u32 v106, v115, v106, s86
	v_bfe_u32 v107, v119, 17, 1
	v_and_b32_e32 v106, 0xfffe0000, v106
	v_add3_u32 v107, v119, v107, s86
	v_and_b32_e32 v107, 0xfffe0000, v107
	v_cvt_pk_bf16_f32 v106, v106, v107
	ds_write_b32 v110, v106 offset:1160
	v_bfe_u32 v106, v116, 17, 1
	v_add3_u32 v106, v116, v106, s86
	v_bfe_u32 v107, v120, 17, 1
	v_and_b32_e32 v106, 0xfffe0000, v106
	v_add3_u32 v107, v120, v107, s86
	v_and_b32_e32 v107, 0xfffe0000, v107
	v_cvt_pk_bf16_f32 v106, v106, v107
	ds_write_b32 v110, v106 offset:1288
	v_bfe_u32 v106, v117, 17, 1
	v_add3_u32 v106, v117, v106, s86
	v_bfe_u32 v107, v121, 17, 1
	v_and_b32_e32 v106, 0xfffe0000, v106
	v_add3_u32 v107, v121, v107, s86
	v_and_b32_e32 v107, 0xfffe0000, v107
	v_cvt_pk_bf16_f32 v106, v106, v107
	ds_write_b32 v110, v106 offset:1416
	s_waitcnt vmcnt(27)
	v_bfe_u32 v106, v122, 17, 1
	v_add3_u32 v106, v122, v106, s86
	s_waitcnt vmcnt(26)
	v_bfe_u32 v107, v126, 17, 1
	v_and_b32_e32 v106, 0xfffe0000, v106
	v_add3_u32 v107, v126, v107, s86
	v_and_b32_e32 v107, 0xfffe0000, v107
	v_cvt_pk_bf16_f32 v106, v106, v107
	ds_write_b32 v110, v106 offset:2064
	v_bfe_u32 v106, v123, 17, 1
	v_add3_u32 v106, v123, v106, s86
	v_bfe_u32 v107, v127, 17, 1
	v_and_b32_e32 v106, 0xfffe0000, v106
	v_add3_u32 v107, v127, v107, s86
	v_and_b32_e32 v107, 0xfffe0000, v107
	v_cvt_pk_bf16_f32 v106, v106, v107
	ds_write_b32 v110, v106 offset:2192
	v_bfe_u32 v106, v124, 17, 1
	v_add3_u32 v106, v124, v106, s86
	v_bfe_u32 v107, v128, 17, 1
	v_and_b32_e32 v106, 0xfffe0000, v106
	v_add3_u32 v107, v128, v107, s86
	v_and_b32_e32 v107, 0xfffe0000, v107
	v_cvt_pk_bf16_f32 v106, v106, v107
	ds_write_b32 v110, v106 offset:2320
	v_bfe_u32 v106, v125, 17, 1
	v_add3_u32 v106, v125, v106, s86
	v_bfe_u32 v107, v129, 17, 1
	v_and_b32_e32 v106, 0xfffe0000, v106
	v_add3_u32 v107, v129, v107, s86
	v_and_b32_e32 v107, 0xfffe0000, v107
	v_cvt_pk_bf16_f32 v106, v106, v107
	ds_write_b32 v110, v106 offset:2448
	s_waitcnt vmcnt(25)
	v_bfe_u32 v106, v98, 17, 1
	v_add3_u32 v98, v98, v106, s86
	s_waitcnt vmcnt(24)
	v_bfe_u32 v106, v102, 17, 1
	v_and_b32_e32 v98, 0xfffe0000, v98
	v_add3_u32 v102, v102, v106, s86
	v_and_b32_e32 v102, 0xfffe0000, v102
	v_cvt_pk_bf16_f32 v98, v98, v102
	ds_write_b32 v110, v98 offset:3096
	v_bfe_u32 v98, v99, 17, 1
	v_add3_u32 v98, v99, v98, s86
	v_bfe_u32 v99, v103, 17, 1
	v_and_b32_e32 v98, 0xfffe0000, v98
	v_add3_u32 v99, v103, v99, s86
	v_and_b32_e32 v99, 0xfffe0000, v99
	v_cvt_pk_bf16_f32 v98, v98, v99
	ds_write_b32 v110, v98 offset:3224
	v_bfe_u32 v98, v100, 17, 1
	v_add3_u32 v98, v100, v98, s86
	v_bfe_u32 v99, v104, 17, 1
	v_and_b32_e32 v98, 0xfffe0000, v98
	v_add3_u32 v99, v104, v99, s86
	v_and_b32_e32 v99, 0xfffe0000, v99
	v_cvt_pk_bf16_f32 v98, v98, v99
	ds_write_b32 v110, v98 offset:3352
	v_bfe_u32 v98, v101, 17, 1
	v_add3_u32 v98, v101, v98, s86
	v_bfe_u32 v99, v105, 17, 1
	v_and_b32_e32 v98, 0xfffe0000, v98
	v_add3_u32 v99, v105, v99, s86
	v_and_b32_e32 v99, 0xfffe0000, v99
	v_cvt_pk_bf16_f32 v98, v98, v99
	ds_write_b32 v110, v98 offset:3480
	s_waitcnt vmcnt(23)
	v_bfe_u32 v98, v90, 17, 1
	v_add3_u32 v90, v90, v98, s86
	s_waitcnt vmcnt(22)
	v_bfe_u32 v98, v94, 17, 1
	v_and_b32_e32 v90, 0xfffe0000, v90
	v_add3_u32 v94, v94, v98, s86
	v_and_b32_e32 v94, 0xfffe0000, v94
	v_cvt_pk_bf16_f32 v90, v90, v94
	ds_write_b32 v110, v90 offset:4128
	v_bfe_u32 v90, v91, 17, 1
	v_add3_u32 v90, v91, v90, s86
	v_bfe_u32 v91, v95, 17, 1
	v_and_b32_e32 v90, 0xfffe0000, v90
	v_add3_u32 v91, v95, v91, s86
	v_and_b32_e32 v91, 0xfffe0000, v91
	v_cvt_pk_bf16_f32 v90, v90, v91
	ds_write_b32 v110, v90 offset:4256
	v_bfe_u32 v90, v92, 17, 1
	v_add3_u32 v90, v92, v90, s86
	v_bfe_u32 v91, v96, 17, 1
	v_and_b32_e32 v90, 0xfffe0000, v90
	v_add3_u32 v91, v96, v91, s86
	v_and_b32_e32 v91, 0xfffe0000, v91
	v_cvt_pk_bf16_f32 v90, v90, v91
	ds_write_b32 v110, v90 offset:4384
	v_bfe_u32 v90, v93, 17, 1
	v_add3_u32 v90, v93, v90, s86
	v_bfe_u32 v91, v97, 17, 1
	v_and_b32_e32 v90, 0xfffe0000, v90
	v_add3_u32 v91, v97, v91, s86
	v_and_b32_e32 v91, 0xfffe0000, v91
	v_cvt_pk_bf16_f32 v90, v90, v91
	ds_write_b32 v110, v90 offset:4512
	s_waitcnt vmcnt(21)
	v_bfe_u32 v90, v82, 17, 1
	v_add3_u32 v82, v82, v90, s86
	s_waitcnt vmcnt(20)
	v_bfe_u32 v90, v86, 17, 1
	v_and_b32_e32 v82, 0xfffe0000, v82
	v_add3_u32 v86, v86, v90, s86
	v_and_b32_e32 v86, 0xfffe0000, v86
	v_cvt_pk_bf16_f32 v82, v82, v86
	ds_write_b32 v110, v82 offset:5160
	v_bfe_u32 v82, v83, 17, 1
	v_add3_u32 v82, v83, v82, s86
	v_bfe_u32 v83, v87, 17, 1
	v_and_b32_e32 v82, 0xfffe0000, v82
	v_add3_u32 v83, v87, v83, s86
	v_and_b32_e32 v83, 0xfffe0000, v83
	v_cvt_pk_bf16_f32 v82, v82, v83
	ds_write_b32 v110, v82 offset:5288
	v_bfe_u32 v82, v84, 17, 1
	v_add3_u32 v82, v84, v82, s86
	v_bfe_u32 v83, v88, 17, 1
	v_and_b32_e32 v82, 0xfffe0000, v82
	v_add3_u32 v83, v88, v83, s86
	v_and_b32_e32 v83, 0xfffe0000, v83
	v_cvt_pk_bf16_f32 v82, v82, v83
	ds_write_b32 v110, v82 offset:5416
	v_bfe_u32 v82, v85, 17, 1
	v_add3_u32 v82, v85, v82, s86
	v_bfe_u32 v83, v89, 17, 1
	v_and_b32_e32 v82, 0xfffe0000, v82
	v_add3_u32 v83, v89, v83, s86
	v_and_b32_e32 v83, 0xfffe0000, v83
	v_cvt_pk_bf16_f32 v82, v82, v83
	ds_write_b32 v110, v82 offset:5544
	s_waitcnt vmcnt(19)
	v_bfe_u32 v82, v74, 17, 1
	v_add3_u32 v74, v74, v82, s86
	s_waitcnt vmcnt(18)
	v_bfe_u32 v82, v78, 17, 1
	v_and_b32_e32 v74, 0xfffe0000, v74
	v_add3_u32 v78, v78, v82, s86
	v_and_b32_e32 v78, 0xfffe0000, v78
	v_cvt_pk_bf16_f32 v74, v74, v78
	ds_write_b32 v110, v74 offset:6192
	v_bfe_u32 v74, v75, 17, 1
	v_add3_u32 v74, v75, v74, s86
	v_bfe_u32 v75, v79, 17, 1
	v_and_b32_e32 v74, 0xfffe0000, v74
	v_add3_u32 v75, v79, v75, s86
	v_and_b32_e32 v75, 0xfffe0000, v75
	v_cvt_pk_bf16_f32 v74, v74, v75
	ds_write_b32 v110, v74 offset:6320
	v_bfe_u32 v74, v76, 17, 1
	v_add3_u32 v74, v76, v74, s86
	v_bfe_u32 v75, v80, 17, 1
	v_and_b32_e32 v74, 0xfffe0000, v74
	v_add3_u32 v75, v80, v75, s86
	v_and_b32_e32 v75, 0xfffe0000, v75
	v_cvt_pk_bf16_f32 v74, v74, v75
	ds_write_b32 v110, v74 offset:6448
	v_bfe_u32 v74, v77, 17, 1
	v_add3_u32 v74, v77, v74, s86
	v_bfe_u32 v75, v81, 17, 1
	v_and_b32_e32 v74, 0xfffe0000, v74
	v_add3_u32 v75, v81, v75, s86
	v_and_b32_e32 v75, 0xfffe0000, v75
	v_cvt_pk_bf16_f32 v74, v74, v75
	ds_write_b32 v110, v74 offset:6576
	s_waitcnt vmcnt(17)
	v_bfe_u32 v74, v66, 17, 1
	v_add3_u32 v66, v66, v74, s86
	s_waitcnt vmcnt(16)
	v_bfe_u32 v74, v70, 17, 1
	v_and_b32_e32 v66, 0xfffe0000, v66
	v_add3_u32 v70, v70, v74, s86
	v_and_b32_e32 v70, 0xfffe0000, v70
	v_cvt_pk_bf16_f32 v66, v66, v70
	ds_write_b32 v110, v66 offset:7224
	v_bfe_u32 v66, v67, 17, 1
	v_add3_u32 v66, v67, v66, s86
	v_bfe_u32 v67, v71, 17, 1
	v_and_b32_e32 v66, 0xfffe0000, v66
	v_add3_u32 v67, v71, v67, s86
	v_and_b32_e32 v67, 0xfffe0000, v67
	v_cvt_pk_bf16_f32 v66, v66, v67
	ds_write_b32 v110, v66 offset:7352
	v_bfe_u32 v66, v68, 17, 1
	v_add3_u32 v66, v68, v66, s86
	v_bfe_u32 v67, v72, 17, 1
	v_and_b32_e32 v66, 0xfffe0000, v66
	v_add3_u32 v67, v72, v67, s86
	v_and_b32_e32 v67, 0xfffe0000, v67
	v_cvt_pk_bf16_f32 v66, v66, v67
	ds_write_b32 v110, v66 offset:7480
	v_bfe_u32 v66, v69, 17, 1
	v_add3_u32 v66, v69, v66, s86
	v_bfe_u32 v67, v73, 17, 1
	v_and_b32_e32 v66, 0xfffe0000, v66
	v_add3_u32 v67, v73, v67, s86
	v_and_b32_e32 v67, 0xfffe0000, v67
	v_cvt_pk_bf16_f32 v66, v66, v67
	ds_write_b32 v110, v66 offset:7608
	s_waitcnt vmcnt(15)
	v_bfe_u32 v66, v58, 17, 1
	v_add3_u32 v58, v58, v66, s86
	s_waitcnt vmcnt(14)
	v_bfe_u32 v66, v62, 17, 1
	v_and_b32_e32 v58, 0xfffe0000, v58
	v_add3_u32 v62, v62, v66, s86
	v_and_b32_e32 v62, 0xfffe0000, v62
	v_cvt_pk_bf16_f32 v58, v58, v62
	ds_write_b32 v110, v58 offset:8256
	v_bfe_u32 v58, v59, 17, 1
	v_add3_u32 v58, v59, v58, s86
	v_bfe_u32 v59, v63, 17, 1
	v_and_b32_e32 v58, 0xfffe0000, v58
	v_add3_u32 v59, v63, v59, s86
	v_and_b32_e32 v59, 0xfffe0000, v59
	v_cvt_pk_bf16_f32 v58, v58, v59
	ds_write_b32 v110, v58 offset:8384
	v_bfe_u32 v58, v60, 17, 1
	v_add3_u32 v58, v60, v58, s86
	v_bfe_u32 v59, v64, 17, 1
	v_and_b32_e32 v58, 0xfffe0000, v58
	v_add3_u32 v59, v64, v59, s86
	v_and_b32_e32 v59, 0xfffe0000, v59
	v_cvt_pk_bf16_f32 v58, v58, v59
	ds_write_b32 v110, v58 offset:8512
	v_bfe_u32 v58, v61, 17, 1
	v_add3_u32 v58, v61, v58, s86
	v_bfe_u32 v59, v65, 17, 1
	v_and_b32_e32 v58, 0xfffe0000, v58
	v_add3_u32 v59, v65, v59, s86
	v_and_b32_e32 v59, 0xfffe0000, v59
	v_cvt_pk_bf16_f32 v58, v58, v59
	ds_write_b32 v110, v58 offset:8640
	s_waitcnt vmcnt(13)
	v_bfe_u32 v58, v50, 17, 1
	v_add3_u32 v50, v50, v58, s86
	s_waitcnt vmcnt(12)
	v_bfe_u32 v58, v54, 17, 1
	v_and_b32_e32 v50, 0xfffe0000, v50
	v_add3_u32 v54, v54, v58, s86
	v_and_b32_e32 v54, 0xfffe0000, v54
	v_cvt_pk_bf16_f32 v50, v50, v54
	ds_write_b32 v110, v50 offset:9288
	v_bfe_u32 v50, v51, 17, 1
	v_add3_u32 v50, v51, v50, s86
	v_bfe_u32 v51, v55, 17, 1
	v_and_b32_e32 v50, 0xfffe0000, v50
	v_add3_u32 v51, v55, v51, s86
	v_and_b32_e32 v51, 0xfffe0000, v51
	v_cvt_pk_bf16_f32 v50, v50, v51
	ds_write_b32 v110, v50 offset:9416
	v_bfe_u32 v50, v52, 17, 1
	v_add3_u32 v50, v52, v50, s86
	v_bfe_u32 v51, v56, 17, 1
	v_and_b32_e32 v50, 0xfffe0000, v50
	v_add3_u32 v51, v56, v51, s86
	v_and_b32_e32 v51, 0xfffe0000, v51
	v_cvt_pk_bf16_f32 v50, v50, v51
	ds_write_b32 v110, v50 offset:9544
	v_bfe_u32 v50, v53, 17, 1
	v_add3_u32 v50, v53, v50, s86
	v_bfe_u32 v51, v57, 17, 1
	v_and_b32_e32 v50, 0xfffe0000, v50
	v_add3_u32 v51, v57, v51, s86
	v_and_b32_e32 v51, 0xfffe0000, v51
	v_cvt_pk_bf16_f32 v50, v50, v51
	ds_write_b32 v110, v50 offset:9672
	s_waitcnt vmcnt(11)
	v_bfe_u32 v50, v42, 17, 1
	v_add3_u32 v42, v42, v50, s86
	s_waitcnt vmcnt(10)
	v_bfe_u32 v50, v46, 17, 1
	v_and_b32_e32 v42, 0xfffe0000, v42
	v_add3_u32 v46, v46, v50, s86
	v_and_b32_e32 v46, 0xfffe0000, v46
	v_cvt_pk_bf16_f32 v42, v42, v46
	ds_write_b32 v110, v42 offset:10320
	v_bfe_u32 v42, v43, 17, 1
	v_add3_u32 v42, v43, v42, s86
	v_bfe_u32 v43, v47, 17, 1
	v_and_b32_e32 v42, 0xfffe0000, v42
	v_add3_u32 v43, v47, v43, s86
	v_and_b32_e32 v43, 0xfffe0000, v43
	v_cvt_pk_bf16_f32 v42, v42, v43
	ds_write_b32 v110, v42 offset:10448
	v_bfe_u32 v42, v44, 17, 1
	v_add3_u32 v42, v44, v42, s86
	v_bfe_u32 v43, v48, 17, 1
	v_and_b32_e32 v42, 0xfffe0000, v42
	v_add3_u32 v43, v48, v43, s86
	v_and_b32_e32 v43, 0xfffe0000, v43
	v_cvt_pk_bf16_f32 v42, v42, v43
	ds_write_b32 v110, v42 offset:10576
	v_bfe_u32 v42, v45, 17, 1
	v_add3_u32 v42, v45, v42, s86
	v_bfe_u32 v43, v49, 17, 1
	v_and_b32_e32 v42, 0xfffe0000, v42
	v_add3_u32 v43, v49, v43, s86
	v_and_b32_e32 v43, 0xfffe0000, v43
	v_cvt_pk_bf16_f32 v42, v42, v43
	ds_write_b32 v110, v42 offset:10704
	s_waitcnt vmcnt(9)
	v_bfe_u32 v42, v34, 17, 1
	v_add3_u32 v34, v34, v42, s86
	s_waitcnt vmcnt(8)
	v_bfe_u32 v42, v38, 17, 1
	v_and_b32_e32 v34, 0xfffe0000, v34
	v_add3_u32 v38, v38, v42, s86
	v_and_b32_e32 v38, 0xfffe0000, v38
	v_cvt_pk_bf16_f32 v34, v34, v38
	ds_write_b32 v110, v34 offset:11352
	v_bfe_u32 v34, v35, 17, 1
	v_add3_u32 v34, v35, v34, s86
	v_bfe_u32 v35, v39, 17, 1
	v_and_b32_e32 v34, 0xfffe0000, v34
	v_add3_u32 v35, v39, v35, s86
	v_and_b32_e32 v35, 0xfffe0000, v35
	v_cvt_pk_bf16_f32 v34, v34, v35
	ds_write_b32 v110, v34 offset:11480
	v_bfe_u32 v34, v36, 17, 1
	v_add3_u32 v34, v36, v34, s86
	v_bfe_u32 v35, v40, 17, 1
	v_and_b32_e32 v34, 0xfffe0000, v34
	v_add3_u32 v35, v40, v35, s86
	v_and_b32_e32 v35, 0xfffe0000, v35
	v_cvt_pk_bf16_f32 v34, v34, v35
	ds_write_b32 v110, v34 offset:11608
	v_bfe_u32 v34, v37, 17, 1
	v_add3_u32 v34, v37, v34, s86
	v_bfe_u32 v35, v41, 17, 1
	v_and_b32_e32 v34, 0xfffe0000, v34
	v_add3_u32 v35, v41, v35, s86
	v_and_b32_e32 v35, 0xfffe0000, v35
	v_cvt_pk_bf16_f32 v34, v34, v35
	ds_write_b32 v110, v34 offset:11736
	s_waitcnt vmcnt(7)
	v_bfe_u32 v34, v26, 17, 1
	v_add3_u32 v26, v26, v34, s86
	s_waitcnt vmcnt(6)
	v_bfe_u32 v34, v30, 17, 1
	v_and_b32_e32 v26, 0xfffe0000, v26
	v_add3_u32 v30, v30, v34, s86
	v_and_b32_e32 v30, 0xfffe0000, v30
	v_cvt_pk_bf16_f32 v26, v26, v30
	ds_write_b32 v110, v26 offset:12384
	v_bfe_u32 v26, v27, 17, 1
	v_add3_u32 v26, v27, v26, s86
	v_bfe_u32 v27, v31, 17, 1
	v_and_b32_e32 v26, 0xfffe0000, v26
	v_add3_u32 v27, v31, v27, s86
	v_and_b32_e32 v27, 0xfffe0000, v27
	v_cvt_pk_bf16_f32 v26, v26, v27
	ds_write_b32 v110, v26 offset:12512
	v_bfe_u32 v26, v28, 17, 1
	v_add3_u32 v26, v28, v26, s86
	v_bfe_u32 v27, v32, 17, 1
	v_and_b32_e32 v26, 0xfffe0000, v26
	v_add3_u32 v27, v32, v27, s86
	v_and_b32_e32 v27, 0xfffe0000, v27
	v_cvt_pk_bf16_f32 v26, v26, v27
	ds_write_b32 v110, v26 offset:12640
	v_bfe_u32 v26, v29, 17, 1
	v_add3_u32 v26, v29, v26, s86
	v_bfe_u32 v27, v33, 17, 1
	v_and_b32_e32 v26, 0xfffe0000, v26
	v_add3_u32 v27, v33, v27, s86
	v_and_b32_e32 v27, 0xfffe0000, v27
	v_cvt_pk_bf16_f32 v26, v26, v27
	ds_write_b32 v110, v26 offset:12768
	s_waitcnt vmcnt(5)
	v_bfe_u32 v26, v18, 17, 1
	v_add3_u32 v18, v18, v26, s86
	s_waitcnt vmcnt(4)
	v_bfe_u32 v26, v22, 17, 1
	v_and_b32_e32 v18, 0xfffe0000, v18
	v_add3_u32 v22, v22, v26, s86
	v_and_b32_e32 v22, 0xfffe0000, v22
	v_cvt_pk_bf16_f32 v18, v18, v22
	ds_write_b32 v110, v18 offset:13416
	v_bfe_u32 v18, v19, 17, 1
	v_add3_u32 v18, v19, v18, s86
	v_bfe_u32 v19, v23, 17, 1
	v_and_b32_e32 v18, 0xfffe0000, v18
	v_add3_u32 v19, v23, v19, s86
	v_and_b32_e32 v19, 0xfffe0000, v19
	v_cvt_pk_bf16_f32 v18, v18, v19
	ds_write_b32 v110, v18 offset:13544
	v_bfe_u32 v18, v20, 17, 1
	v_add3_u32 v18, v20, v18, s86
	v_bfe_u32 v19, v24, 17, 1
	v_and_b32_e32 v18, 0xfffe0000, v18
	v_add3_u32 v19, v24, v19, s86
	v_and_b32_e32 v19, 0xfffe0000, v19
	v_cvt_pk_bf16_f32 v18, v18, v19
	ds_write_b32 v110, v18 offset:13672
	v_bfe_u32 v18, v21, 17, 1
	v_add3_u32 v18, v21, v18, s86
	v_bfe_u32 v19, v25, 17, 1
	v_and_b32_e32 v18, 0xfffe0000, v18
	v_add3_u32 v19, v25, v19, s86
	v_and_b32_e32 v19, 0xfffe0000, v19
	v_cvt_pk_bf16_f32 v18, v18, v19
	ds_write_b32 v110, v18 offset:13800
	s_waitcnt vmcnt(3)
	v_bfe_u32 v18, v10, 17, 1
	v_add3_u32 v10, v10, v18, s86
	s_waitcnt vmcnt(2)
	v_bfe_u32 v18, v14, 17, 1
	v_and_b32_e32 v10, 0xfffe0000, v10
	v_add3_u32 v14, v14, v18, s86
	v_and_b32_e32 v14, 0xfffe0000, v14
	v_cvt_pk_bf16_f32 v10, v10, v14
	ds_write_b32 v110, v10 offset:14448
	v_bfe_u32 v10, v11, 17, 1
	v_add3_u32 v10, v11, v10, s86
	v_bfe_u32 v11, v15, 17, 1
	v_and_b32_e32 v10, 0xfffe0000, v10
	v_add3_u32 v11, v15, v11, s86
	v_and_b32_e32 v11, 0xfffe0000, v11
	v_cvt_pk_bf16_f32 v10, v10, v11
	ds_write_b32 v110, v10 offset:14576
	v_bfe_u32 v10, v12, 17, 1
	v_add3_u32 v10, v12, v10, s86
	v_bfe_u32 v11, v16, 17, 1
	v_and_b32_e32 v10, 0xfffe0000, v10
	v_add3_u32 v11, v16, v11, s86
	v_and_b32_e32 v11, 0xfffe0000, v11
	v_cvt_pk_bf16_f32 v10, v10, v11
	ds_write_b32 v110, v10 offset:14704
	v_bfe_u32 v10, v13, 17, 1
	v_add3_u32 v10, v13, v10, s86
	v_bfe_u32 v11, v17, 17, 1
	v_and_b32_e32 v10, 0xfffe0000, v10
	v_add3_u32 v11, v17, v11, s86
	v_and_b32_e32 v11, 0xfffe0000, v11
	v_cvt_pk_bf16_f32 v10, v10, v11
	ds_write_b32 v110, v10 offset:14832
	s_waitcnt vmcnt(1)
	v_bfe_u32 v10, v2, 17, 1
	v_add3_u32 v2, v2, v10, s86
	s_waitcnt vmcnt(0)
	v_bfe_u32 v10, v6, 17, 1
	v_and_b32_e32 v2, 0xfffe0000, v2
	v_add3_u32 v6, v6, v10, s86
	v_and_b32_e32 v6, 0xfffe0000, v6
	v_cvt_pk_bf16_f32 v2, v2, v6
	ds_write_b32 v110, v2 offset:15480
	v_bfe_u32 v2, v3, 17, 1
	v_add3_u32 v2, v3, v2, s86
	v_bfe_u32 v3, v7, 17, 1
	v_and_b32_e32 v2, 0xfffe0000, v2
	v_add3_u32 v3, v7, v3, s86
	v_and_b32_e32 v3, 0xfffe0000, v3
	v_cvt_pk_bf16_f32 v2, v2, v3
	ds_write_b32 v110, v2 offset:15608
	v_bfe_u32 v2, v4, 17, 1
	v_add3_u32 v2, v4, v2, s86
	v_bfe_u32 v3, v8, 17, 1
	v_and_b32_e32 v2, 0xfffe0000, v2
	v_add3_u32 v3, v8, v3, s86
	v_and_b32_e32 v3, 0xfffe0000, v3
	v_cvt_pk_bf16_f32 v2, v2, v3
	ds_write_b32 v110, v2 offset:15736
	v_bfe_u32 v2, v5, 17, 1
	v_add3_u32 v2, v5, v2, s86
	v_bfe_u32 v3, v9, 17, 1
	v_and_b32_e32 v2, 0xfffe0000, v2
	v_add3_u32 v3, v9, v3, s86
	v_and_b32_e32 v3, 0xfffe0000, v3
	v_cvt_pk_bf16_f32 v2, v2, v3
	ds_write_b32 v110, v2 offset:15864
	s_waitcnt lgkmcnt(0)
	ds_read2_b32 v[20:21], v146 offset1:8
	ds_read2_b32 v[4:5], v146 offset0:129 offset1:137
	v_add_u32_e32 v30, 0x400, v146
	ds_read2_b32 v[22:23], v30 offset0:2 offset1:10
	ds_read2_b32 v[6:7], v30 offset0:131 offset1:139
	v_add_u32_e32 v32, 0x400, v147
	ds_read2_b32 v[24:25], v147 offset1:8
	ds_read2_b32 v[12:13], v147 offset0:129 offset1:137
	ds_read2_b32 v[26:27], v32 offset0:2 offset1:10
	ds_read2_b32 v[14:15], v32 offset0:131 offset1:139
	v_or_b32_e32 v31, s44, v131
	v_lshl_add_u64 v[2:3], s[40:41], 0, v[132:133]
	s_waitcnt lgkmcnt(6)
	v_mov_b32_e32 v9, v4
	v_or3_b32 v4, v31, v145, s2
	v_or_b32_e32 v33, s44, v144
	v_lshl_add_u64 v[2:3], v[2:3], 0, s[4:5]
	v_lshlrev_b32_e32 v132, 7, v4
	v_or3_b32 v4, v33, v145, s2
	v_mov_b32_e32 v8, v20
	s_waitcnt lgkmcnt(5)
	v_mov_b32_e32 v10, v22
	s_waitcnt lgkmcnt(4)
	v_mov_b32_e32 v11, v6
	v_lshl_add_u64 v[16:17], v[2:3], 0, v[132:133]
	v_lshlrev_b32_e32 v132, 7, v4
	global_store_dwordx4 v[16:17], v[8:11], off
	v_lshl_add_u64 v[16:17], v[2:3], 0, v[132:133]
	v_add_u32_e32 v4, 0x400, v149
	s_waitcnt lgkmcnt(3)
	v_mov_b32_e32 v8, v24
	s_waitcnt lgkmcnt(2)
	v_mov_b32_e32 v9, v12
	s_waitcnt lgkmcnt(1)
	v_mov_b32_e32 v10, v26
	s_waitcnt lgkmcnt(0)
	v_mov_b32_e32 v11, v14
	global_store_dwordx4 v[16:17], v[8:11], off
	ds_read2_b32 v[10:11], v4 offset0:2 offset1:131
	v_or3_b32 v4, v31, v148, s2
	ds_read2_b32 v[8:9], v149 offset1:129
	v_lshlrev_b32_e32 v132, 7, v4
	v_add_u32_e32 v4, 0x400, v150
	ds_read2_b32 v[16:17], v150 offset1:129
	ds_read2_b32 v[18:19], v4 offset0:2 offset1:131
	v_or3_b32 v4, v33, v148, s2
	v_lshl_add_u64 v[28:29], v[2:3], 0, v[132:133]
	v_lshlrev_b32_e32 v132, 7, v4
	s_waitcnt lgkmcnt(2)
	global_store_dwordx4 v[28:29], v[8:11], off
	v_mov_b32_e32 v4, v21
	v_mov_b32_e32 v6, v23
	v_lshl_add_u64 v[8:9], v[2:3], 0, v[132:133]
	s_waitcnt lgkmcnt(0)
	global_store_dwordx4 v[8:9], v[16:19], off
	v_or3_b32 v8, v31, v151, s2
	v_lshlrev_b32_e32 v132, 7, v8
	v_lshl_add_u64 v[8:9], v[2:3], 0, v[132:133]
	global_store_dwordx4 v[8:9], v[4:7], off
	v_mov_b32_e32 v12, v25
	v_mov_b32_e32 v14, v27
	v_or3_b32 v4, v33, v151, s2
	v_add_u32_e32 v6, 0x400, v153
	v_lshlrev_b32_e32 v132, 7, v4
	ds_read2_b32 v[4:5], v153 offset1:129
	ds_read2_b32 v[6:7], v6 offset0:2 offset1:131
	v_lshl_add_u64 v[8:9], v[2:3], 0, v[132:133]
	global_store_dwordx4 v[8:9], v[12:15], off
	v_or3_b32 v8, v31, v152, s2
	v_lshlrev_b32_e32 v132, 7, v8
	v_lshl_add_u64 v[8:9], v[2:3], 0, v[132:133]
	s_waitcnt lgkmcnt(0)
	global_store_dwordx4 v[8:9], v[4:7], off
	ds_read2_b32 v[4:5], v154 offset1:129
	v_or3_b32 v8, v33, v152, s2
	v_add_u32_e32 v6, 0x400, v154
	ds_read2_b32 v[6:7], v6 offset0:2 offset1:131
	v_lshlrev_b32_e32 v132, 7, v8
	v_lshl_add_u64 v[12:13], v[2:3], 0, v[132:133]
	ds_read2_b32 v[20:21], v146 offset0:16 offset1:24
	ds_read2_b32 v[8:9], v146 offset0:145 offset1:153
	ds_read2_b32 v[22:23], v30 offset0:18 offset1:26
	ds_read2_b32 v[10:11], v30 offset0:147 offset1:155
	s_mov_b64 s[4:5], 0
	s_waitcnt lgkmcnt(4)
	global_store_dwordx4 v[12:13], v[4:7], off
	ds_read2_b32 v[24:25], v147 offset0:16 offset1:24
	ds_read2_b32 v[12:13], v147 offset0:145 offset1:153
	ds_read2_b32 v[26:27], v32 offset0:18 offset1:26
	ds_read2_b32 v[14:15], v32 offset0:147 offset1:155
	s_waitcnt lgkmcnt(6)
	v_mov_b32_e32 v5, v8
	v_or3_b32 v8, v31, v155, s2
	v_lshlrev_b32_e32 v132, 7, v8
	v_or3_b32 v8, v33, v155, s2
	v_mov_b32_e32 v4, v20
	s_waitcnt lgkmcnt(5)
	v_mov_b32_e32 v6, v22
	s_waitcnt lgkmcnt(4)
	v_mov_b32_e32 v7, v10
	v_lshl_add_u64 v[16:17], v[2:3], 0, v[132:133]
	v_lshlrev_b32_e32 v132, 7, v8
	global_store_dwordx4 v[16:17], v[4:7], off
	v_lshl_add_u64 v[16:17], v[2:3], 0, v[132:133]
	v_or3_b32 v8, v31, v158, s2
	s_waitcnt lgkmcnt(3)
	v_mov_b32_e32 v4, v24
	s_waitcnt lgkmcnt(2)
	v_mov_b32_e32 v5, v12
	s_waitcnt lgkmcnt(1)
	v_mov_b32_e32 v6, v26
	s_waitcnt lgkmcnt(0)
	v_mov_b32_e32 v7, v14
	global_store_dwordx4 v[16:17], v[4:7], off
	ds_read2_b32 v[4:5], v159 offset1:129
	v_lshlrev_b32_e32 v132, 7, v8
	v_add_u32_e32 v6, 0x400, v159
	ds_read2_b32 v[6:7], v6 offset0:2 offset1:131
	v_add_u32_e32 v8, 0x400, v160
	ds_read2_b32 v[16:17], v160 offset1:129
	ds_read2_b32 v[18:19], v8 offset0:2 offset1:131
	v_lshl_add_u64 v[28:29], v[2:3], 0, v[132:133]
	s_waitcnt lgkmcnt(2)
	global_store_dwordx4 v[28:29], v[4:7], off
	v_mov_b32_e32 v8, v21
	v_mov_b32_e32 v10, v23
	v_or3_b32 v4, v33, v158, s2
	v_lshlrev_b32_e32 v132, 7, v4
	v_lshl_add_u64 v[4:5], v[2:3], 0, v[132:133]
	s_waitcnt lgkmcnt(0)
	global_store_dwordx4 v[4:5], v[16:19], off
	v_or3_b32 v4, v31, v161, s2
	v_lshlrev_b32_e32 v132, 7, v4
	v_lshl_add_u64 v[4:5], v[2:3], 0, v[132:133]
	global_store_dwordx4 v[4:5], v[8:11], off
	v_or3_b32 v4, v33, v161, s2
	v_lshlrev_b32_e32 v132, 7, v4
	v_mov_b32_e32 v12, v25
	v_mov_b32_e32 v14, v27
	v_lshl_add_u64 v[4:5], v[2:3], 0, v[132:133]
	v_add_u32_e32 v6, 0x400, v163
	global_store_dwordx4 v[4:5], v[12:15], off
	ds_read2_b32 v[4:5], v163 offset1:129
	ds_read2_b32 v[6:7], v6 offset0:2 offset1:131
	v_or3_b32 v8, v31, v162, s2
	v_add_u32_e32 v10, 0x400, v164
	v_lshlrev_b32_e32 v132, 7, v8
	ds_read2_b32 v[8:9], v164 offset1:129
	ds_read2_b32 v[10:11], v10 offset0:2 offset1:131
	v_lshl_add_u64 v[12:13], v[2:3], 0, v[132:133]
	s_waitcnt lgkmcnt(2)
	global_store_dwordx4 v[12:13], v[4:7], off
	s_nop 1
	v_or3_b32 v4, v33, v162, s2
	v_lshlrev_b32_e32 v132, 7, v4
	v_lshl_add_u64 v[2:3], v[2:3], 0, v[132:133]
	s_waitcnt lgkmcnt(0)
	global_store_dwordx4 v[2:3], v[8:11], off
	s_waitcnt lgkmcnt(0)

.LBB0_26:
	s_andn2_b64 vcc, exec, s[4:5]
	s_cbranch_vccnz .LBB0_60
	s_mul_i32 s4, s42, 0x1c00000
	s_mul_hi_i32 s2, s42, 0x1c00000
	s_add_u32 s4, s6, s4
	s_addc_u32 s5, s7, s2
	s_lshl_b32 s44, s42, 11
	s_ashr_i32 s45, s44, 31
	s_lshl_b64 s[44:45], s[44:45], 2
	s_add_u32 s44, s26, s44
	s_addc_u32 s45, s27, s45
	s_add_i32 s2, s70, 0xea00
	s_bfe_u32 s38, s2, 0xe0002
	s_mulk_i32 s38, 0x4925
	s_lshr_b32 s71, s38, 17
	s_mul_i32 s38, s71, 28
	s_sub_i32 s38, s2, s38
	s_and_b32 vcc_lo, s38, 0xffff
	s_lshl_b32 s43, vcc_lo, 7
	s_bfe_u32 s38, s38, 0xf0001
	s_lshl_b32 vcc_lo, vcc_lo, 9
	s_add_i32 vcc_hi, s38, -10
	s_and_b32 vcc_lo, vcc_lo, 0x200
	s_lshl_b32 s38, s38, 7
	s_add_i32 s38, s38, vcc_lo
	s_lshl_b32 s2, s71, 6
	s_addk_i32 s38, 0x300
	s_cmp_lt_u32 vcc_hi, -4
	s_cselect_b32 s38, s43, s38
	v_or_b32_e32 v137, s2, v165
	v_mov_b64_e32 v[2:3], s[4:5]
	s_movk_i32 s4, 0x3800
	v_mad_u64_u32 v[2:3], s[4:5], v137, s4, v[2:3]
	s_lshl_b32 s38, s38, 2
	v_lshl_add_u64 v[2:3], v[2:3], 0, s[38:39]
	v_lshlrev_b32_e32 v132, 2, v130
	v_lshl_add_u64 v[2:3], v[2:3], 0, v[132:133]
	s_movk_i32 s4, 0x3000
	v_add_co_u32_e32 v4, vcc, s4, v2
	s_mov_b32 s4, 0xe000
	s_nop 0
	v_addc_co_u32_e32 v5, vcc, 0, v3, vcc
	global_load_dwordx4 v[126:129], v[2:3], off
	global_load_dwordx4 v[122:125], v[4:5], off offset:2048
	v_add_co_u32_e32 v4, vcc, s4, v2
	s_mov_b32 s4, 0x11000
	s_nop 0
	v_addc_co_u32_e32 v5, vcc, 0, v3, vcc
	v_add_co_u32_e32 v6, vcc, s4, v2
	s_mov_b32 s4, 0x1c000
	s_nop 0
	v_addc_co_u32_e32 v7, vcc, 0, v3, vcc
	global_load_dwordx4 v[118:121], v[4:5], off
	global_load_dwordx4 v[114:117], v[6:7], off offset:2048
	v_add_co_u32_e32 v4, vcc, s4, v2
	s_mov_b32 s4, 0x1f000
	s_nop 0
	v_addc_co_u32_e32 v5, vcc, 0, v3, vcc
	v_add_co_u32_e32 v6, vcc, s4, v2
	s_mov_b32 s4, 0x2d000
	s_nop 0
	v_addc_co_u32_e32 v7, vcc, 0, v3, vcc
	global_load_dwordx4 v[110:113], v[4:5], off
	global_load_dwordx4 v[106:109], v[6:7], off offset:2048
	v_add_co_u32_e32 v4, vcc, s58, v2
	v_cndmask_b32_e64 v132, 0, 1, s[0:1]
	s_nop 0
	v_addc_co_u32_e32 v5, vcc, 0, v3, vcc
	v_add_co_u32_e32 v6, vcc, s4, v2
	s_mov_b32 s4, 0x3b000
	s_nop 0
	v_addc_co_u32_e32 v7, vcc, 0, v3, vcc
	global_load_dwordx4 v[102:105], v[4:5], off
	global_load_dwordx4 v[98:101], v[6:7], off offset:2048
	v_add_co_u32_e32 v4, vcc, s61, v2
	v_mov_b32_e32 v136, 1.0
	s_nop 0
	v_addc_co_u32_e32 v5, vcc, 0, v3, vcc
	v_add_co_u32_e32 v6, vcc, s4, v2
	s_mov_b32 s4, 0x46000
	s_nop 0
	v_addc_co_u32_e32 v7, vcc, 0, v3, vcc
	global_load_dwordx4 v[94:97], v[4:5], off
	global_load_dwordx4 v[90:93], v[6:7], off offset:2048
	v_add_co_u32_e32 v4, vcc, s4, v2
	s_mov_b32 s4, 0x49000
	s_nop 0
	v_addc_co_u32_e32 v5, vcc, 0, v3, vcc
	v_add_co_u32_e32 v6, vcc, s4, v2
	s_mov_b32 s4, 0x54000
	s_nop 0
	v_addc_co_u32_e32 v7, vcc, 0, v3, vcc
	global_load_dwordx4 v[86:89], v[4:5], off
	global_load_dwordx4 v[82:85], v[6:7], off offset:2048
	v_add_co_u32_e32 v4, vcc, s4, v2
	s_mov_b32 s4, 0x57000
	s_nop 0
	v_addc_co_u32_e32 v5, vcc, 0, v3, vcc
	v_add_co_u32_e32 v6, vcc, s4, v2
	s_mov_b32 s4, 0x65000
	s_nop 0
	v_addc_co_u32_e32 v7, vcc, 0, v3, vcc
	global_load_dwordx4 v[78:81], v[4:5], off
	global_load_dwordx4 v[74:77], v[6:7], off offset:2048
	v_add_co_u32_e32 v4, vcc, s79, v2
	v_mov_b32_e32 v138, 1.0
	s_nop 0
	v_addc_co_u32_e32 v5, vcc, 0, v3, vcc
	v_add_co_u32_e32 v6, vcc, s4, v2
	s_mov_b32 s4, 0x73000
	s_nop 0
	v_addc_co_u32_e32 v7, vcc, 0, v3, vcc
	global_load_dwordx4 v[70:73], v[4:5], off
	global_load_dwordx4 v[66:69], v[6:7], off offset:2048
	v_add_co_u32_e32 v4, vcc, s82, v2
	v_mov_b32_e32 v139, 1.0
	s_nop 0
	v_addc_co_u32_e32 v5, vcc, 0, v3, vcc
	v_add_co_u32_e32 v6, vcc, s4, v2
	s_mov_b32 s4, 0x7e000
	s_nop 0
	v_addc_co_u32_e32 v7, vcc, 0, v3, vcc
	global_load_dwordx4 v[62:65], v[4:5], off
	global_load_dwordx4 v[58:61], v[6:7], off offset:2048
	v_add_co_u32_e32 v4, vcc, s4, v2
	s_mov_b32 s4, 0x81000
	s_nop 0
	v_addc_co_u32_e32 v5, vcc, 0, v3, vcc
	v_add_co_u32_e32 v6, vcc, s4, v2
	s_mov_b32 s4, 0x8c000
	s_nop 0
	v_addc_co_u32_e32 v7, vcc, 0, v3, vcc
	global_load_dwordx4 v[54:57], v[4:5], off
	global_load_dwordx4 v[50:53], v[6:7], off offset:2048
	v_add_co_u32_e32 v4, vcc, s4, v2
	s_mov_b32 s4, 0x9a000
	s_nop 0
	v_addc_co_u32_e32 v5, vcc, 0, v3, vcc
	v_add_co_u32_e32 v6, vcc, s87, v2
	s_nop 1
	v_addc_co_u32_e32 v7, vcc, 0, v3, vcc
	global_load_dwordx4 v[46:49], v[4:5], off
	global_load_dwordx4 v[42:45], v[6:7], off offset:2048
	v_add_co_u32_e32 v4, vcc, s4, v2
	s_mov_b32 s4, 0x9d000
	s_nop 0
	v_addc_co_u32_e32 v5, vcc, 0, v3, vcc
	v_add_co_u32_e32 v6, vcc, s4, v2
	s_mov_b32 s4, 0xa8000
	s_nop 0
	v_addc_co_u32_e32 v7, vcc, 0, v3, vcc
	global_load_dwordx4 v[38:41], v[4:5], off
	global_load_dwordx4 v[34:37], v[6:7], off offset:2048
	v_add_co_u32_e32 v4, vcc, s4, v2
	s_mov_b32 s4, 0xab000
	s_nop 0
	v_addc_co_u32_e32 v5, vcc, 0, v3, vcc
	v_add_co_u32_e32 v6, vcc, s4, v2
	s_mov_b32 s4, 0xb6000
	s_nop 0
	v_addc_co_u32_e32 v7, vcc, 0, v3, vcc
	global_load_dwordx4 v[30:33], v[4:5], off
	global_load_dwordx4 v[26:29], v[6:7], off offset:2048
	v_add_co_u32_e32 v4, vcc, s4, v2
	s_mov_b32 s4, 0xb9000
	s_nop 0
	v_addc_co_u32_e32 v5, vcc, 0, v3, vcc
	v_add_co_u32_e32 v6, vcc, s4, v2
	s_mov_b32 s4, 0xc4000
	s_nop 0
	v_addc_co_u32_e32 v7, vcc, 0, v3, vcc
	global_load_dwordx4 v[22:25], v[4:5], off
	global_load_dwordx4 v[18:21], v[6:7], off offset:2048
	v_add_co_u32_e32 v4, vcc, s4, v2
	v_cmp_ne_u32_e64 s[4:5], 1, v132
	s_nop 0
	v_addc_co_u32_e32 v5, vcc, 0, v3, vcc
	v_add_co_u32_e32 v6, vcc, 0xc7000, v2
	s_nop 1
	v_addc_co_u32_e32 v7, vcc, 0, v3, vcc
	global_load_dwordx4 v[14:17], v[4:5], off
	global_load_dwordx4 v[10:13], v[6:7], off offset:2048
	v_add_co_u32_e32 v4, vcc, 0xd2000, v2
	s_nop 1
	v_addc_co_u32_e32 v5, vcc, 0, v3, vcc
	v_add_co_u32_e32 v2, vcc, 0xd5000, v2
	s_nop 1
	v_addc_co_u32_e32 v3, vcc, 0, v3, vcc
	global_load_dwordx4 v[6:9], v[4:5], off
	s_nop 0
	global_load_dwordx4 v[2:5], v[2:3], off offset:2048
	s_andn2_b64 vcc, exec, s[0:1]
	s_cbranch_vccnz .LBB0_29
	v_lshlrev_b32_e32 v132, 2, v137
	global_load_dwordx2 v[138:139], v132, s[44:45]
	v_or_b32_e32 v228, s2, v166
	v_lshlrev_b32_e32 v228, 2, v228
	global_load_dwordx2 v[192:193], v228, s[44:45]
	v_or_b32_e32 v228, s2, v167
	v_lshlrev_b32_e32 v228, 2, v228
	global_load_dwordx2 v[194:195], v228, s[44:45]
	v_or_b32_e32 v228, s2, v169
	v_lshlrev_b32_e32 v228, 2, v228
	global_load_dwordx2 v[196:197], v228, s[44:45]
	v_or_b32_e32 v228, s2, v171
	v_lshlrev_b32_e32 v228, 2, v228
	global_load_dwordx2 v[198:199], v228, s[44:45]
	v_or_b32_e32 v228, s2, v173
	v_lshlrev_b32_e32 v228, 2, v228
	global_load_dwordx2 v[200:201], v228, s[44:45]
	v_or_b32_e32 v228, s2, v175
	v_lshlrev_b32_e32 v228, 2, v228
	global_load_dwordx2 v[202:203], v228, s[44:45]
	v_or_b32_e32 v228, s2, v177
	v_lshlrev_b32_e32 v228, 2, v228
	global_load_dwordx2 v[204:205], v228, s[44:45]
	v_or_b32_e32 v228, s2, v179
	v_lshlrev_b32_e32 v228, 2, v228
	global_load_dwordx2 v[206:207], v228, s[44:45]
	v_or_b32_e32 v228, s2, v181
	v_lshlrev_b32_e32 v228, 2, v228
	global_load_dwordx2 v[208:209], v228, s[44:45]
	v_or_b32_e32 v228, s2, v183
	v_lshlrev_b32_e32 v228, 2, v228
	global_load_dwordx2 v[210:211], v228, s[44:45]
	v_or_b32_e32 v228, s2, v185
	v_lshlrev_b32_e32 v228, 2, v228
	global_load_dwordx2 v[212:213], v228, s[44:45]
	v_or_b32_e32 v228, s2, v187
	v_lshlrev_b32_e32 v228, 2, v228
	global_load_dwordx2 v[214:215], v228, s[44:45]
	v_or_b32_e32 v228, s2, v188
	v_lshlrev_b32_e32 v228, 2, v228
	global_load_dwordx2 v[216:217], v228, s[44:45]
	v_or_b32_e32 v228, s2, v189
	v_lshlrev_b32_e32 v228, 2, v228
	global_load_dwordx2 v[218:219], v228, s[44:45]
	v_or_b32_e32 v228, s2, v190
	v_lshlrev_b32_e32 v228, 2, v228
	global_load_dwordx2 v[230:231], v228, s[44:45]
.LBB0_29:
	s_waitcnt vmcnt(0)
	v_mul_f32_e32 v126, v126, v138
	v_bfe_u32 v132, v126, 17, 1
	v_mul_f32_e32 v122, v122, v139
	v_add3_u32 v126, v126, v132, s86
	v_bfe_u32 v132, v122, 17, 1
	v_add3_u32 v122, v122, v132, s86
	v_and_b32_e32 v126, 0xfffe0000, v126
	v_and_b32_e32 v122, 0xfffe0000, v122
	v_cvt_pk_bf16_f32 v126, v126, v122
	v_add_u32_e32 v122, v142, v143
	ds_write_b32 v122, v126
	v_mul_f32_e32 v126, v127, v138
	v_bfe_u32 v127, v126, 17, 1
	v_mul_f32_e32 v123, v123, v139
	v_add3_u32 v126, v126, v127, s86
	v_bfe_u32 v127, v123, 17, 1
	v_add3_u32 v123, v123, v127, s86
	v_and_b32_e32 v123, 0xfffe0000, v123
	v_and_b32_e32 v126, 0xfffe0000, v126
	v_cvt_pk_bf16_f32 v123, v126, v123
	ds_write_b32 v122, v123 offset:128
	v_mul_f32_e32 v123, v128, v138
	v_bfe_u32 v126, v123, 17, 1
	v_mul_f32_e32 v124, v124, v139
	v_add3_u32 v123, v123, v126, s86
	v_bfe_u32 v126, v124, 17, 1
	v_and_b32_e32 v123, 0xfffe0000, v123
	v_add3_u32 v124, v124, v126, s86
	v_and_b32_e32 v124, 0xfffe0000, v124
	v_cvt_pk_bf16_f32 v123, v123, v124
	ds_write_b32 v122, v123 offset:256
	v_mul_f32_e32 v123, v129, v138
	v_bfe_u32 v124, v123, 17, 1
	v_add3_u32 v123, v123, v124, s86
	v_mul_f32_e32 v124, v125, v139
	v_bfe_u32 v125, v124, 17, 1
	v_and_b32_e32 v123, 0xfffe0000, v123
	v_add3_u32 v124, v124, v125, s86
	s_and_b64 vcc, exec, s[4:5]
	v_mov_b32_e32 v137, 1.0
	v_and_b32_e32 v124, 0xfffe0000, v124
	v_cvt_pk_bf16_f32 v123, v123, v124
	ds_write_b32 v122, v123 offset:384
	s_cbranch_vccnz .LBB0_31
	v_mov_b32_e32 v136, v192
	v_mov_b32_e32 v137, v193
	s_nop 0
.LBB0_31:
	s_waitcnt vmcnt(0)
	v_mul_f32_e32 v118, v118, v136
	v_bfe_u32 v123, v118, 17, 1
	v_mul_f32_e32 v114, v114, v137
	v_add3_u32 v118, v118, v123, s86
	v_bfe_u32 v123, v114, 17, 1
	v_add3_u32 v114, v114, v123, s86
	v_and_b32_e32 v114, 0xfffe0000, v114
	v_and_b32_e32 v118, 0xfffe0000, v118
	v_cvt_pk_bf16_f32 v114, v118, v114
	ds_write_b32 v122, v114 offset:1032
	v_mul_f32_e32 v114, v119, v136
	v_bfe_u32 v118, v114, 17, 1
	v_mul_f32_e32 v115, v115, v137
	v_add3_u32 v114, v114, v118, s86
	v_bfe_u32 v118, v115, 17, 1
	v_and_b32_e32 v114, 0xfffe0000, v114
	v_add3_u32 v115, v115, v118, s86
	v_and_b32_e32 v115, 0xfffe0000, v115
	v_cvt_pk_bf16_f32 v114, v114, v115
	ds_write_b32 v122, v114 offset:1160
	v_mul_f32_e32 v114, v120, v136
	v_bfe_u32 v115, v114, 17, 1
	v_add3_u32 v114, v114, v115, s86
	v_mul_f32_e32 v115, v116, v137
	v_bfe_u32 v116, v115, 17, 1
	v_and_b32_e32 v114, 0xfffe0000, v114
	v_add3_u32 v115, v115, v116, s86
	v_and_b32_e32 v115, 0xfffe0000, v115
	v_cvt_pk_bf16_f32 v114, v114, v115
	ds_write_b32 v122, v114 offset:1288
	v_mul_f32_e32 v114, v121, v136
	v_bfe_u32 v115, v114, 17, 1
	v_add3_u32 v114, v114, v115, s86
	v_mul_f32_e32 v115, v117, v137
	v_bfe_u32 v116, v115, 17, 1
	v_and_b32_e32 v114, 0xfffe0000, v114
	v_add3_u32 v115, v115, v116, s86
	v_and_b32_e32 v115, 0xfffe0000, v115
	v_cvt_pk_bf16_f32 v114, v114, v115
	ds_write_b32 v122, v114 offset:1416
	v_mov_b32_e32 v114, 1.0
	s_and_b64 vcc, exec, s[4:5]
	v_mov_b32_e32 v116, 1.0
	v_mov_b32_e32 v117, 1.0
	s_cbranch_vccnz .LBB0_33
	v_mov_b32_e32 v116, v194
	v_mov_b32_e32 v117, v195
	s_nop 0
.LBB0_33:
	s_waitcnt vmcnt(0)
	v_mul_f32_e32 v110, v110, v116
	v_bfe_u32 v115, v110, 17, 1
	v_mul_f32_e32 v106, v106, v117
	v_add3_u32 v110, v110, v115, s86
	v_bfe_u32 v115, v106, 17, 1
	v_add3_u32 v106, v106, v115, s86
	v_and_b32_e32 v110, 0xfffe0000, v110
	v_and_b32_e32 v106, 0xfffe0000, v106
	v_cvt_pk_bf16_f32 v106, v110, v106
	v_add_u32_e32 v110, v142, v168
	ds_write_b32 v110, v106
	v_mul_f32_e32 v106, v111, v116
	v_bfe_u32 v111, v106, 17, 1
	v_mul_f32_e32 v107, v107, v117
	v_add3_u32 v106, v106, v111, s86
	v_bfe_u32 v111, v107, 17, 1
	v_and_b32_e32 v106, 0xfffe0000, v106
	v_add3_u32 v107, v107, v111, s86
	v_and_b32_e32 v107, 0xfffe0000, v107
	v_cvt_pk_bf16_f32 v106, v106, v107
	ds_write_b32 v110, v106 offset:128
	v_mul_f32_e32 v106, v112, v116
	v_bfe_u32 v107, v106, 17, 1
	v_add3_u32 v106, v106, v107, s86
	v_mul_f32_e32 v107, v108, v117
	v_bfe_u32 v108, v107, 17, 1
	v_and_b32_e32 v106, 0xfffe0000, v106
	v_add3_u32 v107, v107, v108, s86
	v_and_b32_e32 v107, 0xfffe0000, v107
	v_cvt_pk_bf16_f32 v106, v106, v107
	ds_write_b32 v110, v106 offset:256
	v_mul_f32_e32 v106, v113, v116
	v_bfe_u32 v107, v106, 17, 1
	v_add3_u32 v106, v106, v107, s86
	v_mul_f32_e32 v107, v109, v117
	v_bfe_u32 v108, v107, 17, 1
	v_and_b32_e32 v106, 0xfffe0000, v106
	v_add3_u32 v107, v107, v108, s86
	s_and_b64 vcc, exec, s[4:5]
	v_mov_b32_e32 v115, 1.0
	v_and_b32_e32 v107, 0xfffe0000, v107
	v_cvt_pk_bf16_f32 v106, v106, v107
	ds_write_b32 v110, v106 offset:384
	s_cbranch_vccnz .LBB0_35
	v_mov_b32_e32 v114, v196
	v_mov_b32_e32 v115, v197
	s_nop 0
.LBB0_35:
	s_waitcnt vmcnt(0)
	v_mul_f32_e32 v102, v102, v114
	v_bfe_u32 v106, v102, 17, 1
	v_mul_f32_e32 v98, v98, v115
	v_add3_u32 v102, v102, v106, s86
	v_bfe_u32 v106, v98, 17, 1
	v_add3_u32 v98, v98, v106, s86
	v_and_b32_e32 v102, 0xfffe0000, v102
	v_and_b32_e32 v98, 0xfffe0000, v98
	v_cvt_pk_bf16_f32 v98, v102, v98
	v_add_u32_e32 v102, v142, v170
	ds_write_b32 v102, v98
	v_mul_f32_e32 v98, v103, v114
	v_bfe_u32 v103, v98, 17, 1
	v_mul_f32_e32 v99, v99, v115
	v_add3_u32 v98, v98, v103, s86
	v_bfe_u32 v103, v99, 17, 1
	v_and_b32_e32 v98, 0xfffe0000, v98
	v_add3_u32 v99, v99, v103, s86
	v_and_b32_e32 v99, 0xfffe0000, v99
	v_cvt_pk_bf16_f32 v98, v98, v99
	ds_write_b32 v102, v98 offset:128
	v_mul_f32_e32 v98, v104, v114
	v_bfe_u32 v99, v98, 17, 1
	v_add3_u32 v98, v98, v99, s86
	v_mul_f32_e32 v99, v100, v115
	v_bfe_u32 v100, v99, 17, 1
	v_and_b32_e32 v98, 0xfffe0000, v98
	v_add3_u32 v99, v99, v100, s86
	v_and_b32_e32 v99, 0xfffe0000, v99
	v_cvt_pk_bf16_f32 v98, v98, v99
	ds_write_b32 v102, v98 offset:256
	v_mul_f32_e32 v98, v105, v114
	v_bfe_u32 v99, v98, 17, 1
	v_add3_u32 v98, v98, v99, s86
	v_mul_f32_e32 v99, v101, v115
	v_bfe_u32 v100, v99, 17, 1
	v_and_b32_e32 v98, 0xfffe0000, v98
	v_add3_u32 v99, v99, v100, s86
	v_and_b32_e32 v99, 0xfffe0000, v99
	v_cvt_pk_bf16_f32 v98, v98, v99
	ds_write_b32 v102, v98 offset:384
	v_mov_b32_e32 v98, 1.0
	s_and_b64 vcc, exec, s[4:5]
	v_mov_b32_e32 v100, 1.0
	v_mov_b32_e32 v101, 1.0
	s_cbranch_vccnz .LBB0_37
	v_mov_b32_e32 v100, v198
	v_mov_b32_e32 v101, v199
	s_nop 0
.LBB0_37:
	s_waitcnt vmcnt(0)
	v_mul_f32_e32 v94, v94, v100
	v_bfe_u32 v99, v94, 17, 1
	v_mul_f32_e32 v90, v90, v101
	v_add3_u32 v94, v94, v99, s86
	v_bfe_u32 v99, v90, 17, 1
	v_add3_u32 v90, v90, v99, s86
	v_and_b32_e32 v94, 0xfffe0000, v94
	v_and_b32_e32 v90, 0xfffe0000, v90
	v_cvt_pk_bf16_f32 v90, v94, v90
	v_add_u32_e32 v94, v142, v172
	ds_write_b32 v94, v90
	v_mul_f32_e32 v90, v95, v100
	v_bfe_u32 v95, v90, 17, 1
	v_mul_f32_e32 v91, v91, v101
	v_add3_u32 v90, v90, v95, s86
	v_bfe_u32 v95, v91, 17, 1
	v_and_b32_e32 v90, 0xfffe0000, v90
	v_add3_u32 v91, v91, v95, s86
	v_and_b32_e32 v91, 0xfffe0000, v91
	v_cvt_pk_bf16_f32 v90, v90, v91
	ds_write_b32 v94, v90 offset:128
	v_mul_f32_e32 v90, v96, v100
	v_bfe_u32 v91, v90, 17, 1
	v_add3_u32 v90, v90, v91, s86
	v_mul_f32_e32 v91, v92, v101
	v_bfe_u32 v92, v91, 17, 1
	v_and_b32_e32 v90, 0xfffe0000, v90
	v_add3_u32 v91, v91, v92, s86
	v_and_b32_e32 v91, 0xfffe0000, v91
	v_cvt_pk_bf16_f32 v90, v90, v91
	ds_write_b32 v94, v90 offset:256
	v_mul_f32_e32 v90, v97, v100
	v_bfe_u32 v91, v90, 17, 1
	v_add3_u32 v90, v90, v91, s86
	v_mul_f32_e32 v91, v93, v101
	v_bfe_u32 v92, v91, 17, 1
	v_and_b32_e32 v90, 0xfffe0000, v90
	v_add3_u32 v91, v91, v92, s86
	s_and_b64 vcc, exec, s[4:5]
	v_mov_b32_e32 v99, 1.0
	v_and_b32_e32 v91, 0xfffe0000, v91
	v_cvt_pk_bf16_f32 v90, v90, v91
	ds_write_b32 v94, v90 offset:384
	s_cbranch_vccnz .LBB0_39
	v_mov_b32_e32 v98, v200
	v_mov_b32_e32 v99, v201
	s_nop 0
.LBB0_39:
	s_waitcnt vmcnt(0)
	v_mul_f32_e32 v86, v86, v98
	v_bfe_u32 v90, v86, 17, 1
	v_mul_f32_e32 v82, v82, v99
	v_add3_u32 v86, v86, v90, s86
	v_bfe_u32 v90, v82, 17, 1
	v_add3_u32 v82, v82, v90, s86
	v_and_b32_e32 v86, 0xfffe0000, v86
	v_and_b32_e32 v82, 0xfffe0000, v82
	v_cvt_pk_bf16_f32 v82, v86, v82
	v_add_u32_e32 v86, v142, v174
	ds_write_b32 v86, v82
	v_mul_f32_e32 v82, v87, v98
	v_bfe_u32 v87, v82, 17, 1
	v_mul_f32_e32 v83, v83, v99
	v_add3_u32 v82, v82, v87, s86
	v_bfe_u32 v87, v83, 17, 1
	v_and_b32_e32 v82, 0xfffe0000, v82
	v_add3_u32 v83, v83, v87, s86
	v_and_b32_e32 v83, 0xfffe0000, v83
	v_cvt_pk_bf16_f32 v82, v82, v83
	ds_write_b32 v86, v82 offset:128
	v_mul_f32_e32 v82, v88, v98
	v_bfe_u32 v83, v82, 17, 1
	v_add3_u32 v82, v82, v83, s86
	v_mul_f32_e32 v83, v84, v99
	v_bfe_u32 v84, v83, 17, 1
	v_and_b32_e32 v82, 0xfffe0000, v82
	v_add3_u32 v83, v83, v84, s86
	v_and_b32_e32 v83, 0xfffe0000, v83
	v_cvt_pk_bf16_f32 v82, v82, v83
	ds_write_b32 v86, v82 offset:256
	v_mul_f32_e32 v82, v89, v98
	v_bfe_u32 v83, v82, 17, 1
	v_add3_u32 v82, v82, v83, s86
	v_mul_f32_e32 v83, v85, v99
	v_bfe_u32 v84, v83, 17, 1
	v_and_b32_e32 v82, 0xfffe0000, v82
	v_add3_u32 v83, v83, v84, s86
	v_and_b32_e32 v83, 0xfffe0000, v83
	v_cvt_pk_bf16_f32 v82, v82, v83
	ds_write_b32 v86, v82 offset:384
	v_mov_b32_e32 v82, 1.0
	s_and_b64 vcc, exec, s[4:5]
	v_mov_b32_e32 v84, 1.0
	v_mov_b32_e32 v85, 1.0
	s_cbranch_vccnz .LBB0_41
	v_mov_b32_e32 v84, v202
	v_mov_b32_e32 v85, v203
	s_nop 0
.LBB0_41:
	s_waitcnt vmcnt(0)
	v_mul_f32_e32 v78, v78, v84
	v_bfe_u32 v83, v78, 17, 1
	v_mul_f32_e32 v74, v74, v85
	v_add3_u32 v78, v78, v83, s86
	v_bfe_u32 v83, v74, 17, 1
	v_add3_u32 v74, v74, v83, s86
	v_and_b32_e32 v78, 0xfffe0000, v78
	v_and_b32_e32 v74, 0xfffe0000, v74
	v_cvt_pk_bf16_f32 v74, v78, v74
	v_add_u32_e32 v78, v142, v176
	ds_write_b32 v78, v74
	v_mul_f32_e32 v74, v79, v84
	v_bfe_u32 v79, v74, 17, 1
	v_mul_f32_e32 v75, v75, v85
	v_add3_u32 v74, v74, v79, s86
	v_bfe_u32 v79, v75, 17, 1
	v_and_b32_e32 v74, 0xfffe0000, v74
	v_add3_u32 v75, v75, v79, s86
	v_and_b32_e32 v75, 0xfffe0000, v75
	v_cvt_pk_bf16_f32 v74, v74, v75
	ds_write_b32 v78, v74 offset:128
	v_mul_f32_e32 v74, v80, v84
	v_bfe_u32 v75, v74, 17, 1
	v_add3_u32 v74, v74, v75, s86
	v_mul_f32_e32 v75, v76, v85
	v_bfe_u32 v76, v75, 17, 1
	v_and_b32_e32 v74, 0xfffe0000, v74
	v_add3_u32 v75, v75, v76, s86
	v_and_b32_e32 v75, 0xfffe0000, v75
	v_cvt_pk_bf16_f32 v74, v74, v75
	ds_write_b32 v78, v74 offset:256
	v_mul_f32_e32 v74, v81, v84
	v_bfe_u32 v75, v74, 17, 1
	v_add3_u32 v74, v74, v75, s86
	v_mul_f32_e32 v75, v77, v85
	v_bfe_u32 v76, v75, 17, 1
	v_and_b32_e32 v74, 0xfffe0000, v74
	v_add3_u32 v75, v75, v76, s86
	s_and_b64 vcc, exec, s[4:5]
	v_mov_b32_e32 v83, 1.0
	v_and_b32_e32 v75, 0xfffe0000, v75
	v_cvt_pk_bf16_f32 v74, v74, v75
	ds_write_b32 v78, v74 offset:384
	s_cbranch_vccnz .LBB0_43
	v_mov_b32_e32 v82, v204
	v_mov_b32_e32 v83, v205
	s_nop 0
.LBB0_43:
	s_waitcnt vmcnt(0)
	v_mul_f32_e32 v70, v70, v82
	v_bfe_u32 v74, v70, 17, 1
	v_mul_f32_e32 v66, v66, v83
	v_add3_u32 v70, v70, v74, s86
	v_bfe_u32 v74, v66, 17, 1
	v_add3_u32 v66, v66, v74, s86
	v_and_b32_e32 v70, 0xfffe0000, v70
	v_and_b32_e32 v66, 0xfffe0000, v66
	v_cvt_pk_bf16_f32 v66, v70, v66
	v_add_u32_e32 v70, v142, v178
	ds_write_b32 v70, v66
	v_mul_f32_e32 v66, v71, v82
	v_bfe_u32 v71, v66, 17, 1
	v_mul_f32_e32 v67, v67, v83
	v_add3_u32 v66, v66, v71, s86
	v_bfe_u32 v71, v67, 17, 1
	v_and_b32_e32 v66, 0xfffe0000, v66
	v_add3_u32 v67, v67, v71, s86
	v_and_b32_e32 v67, 0xfffe0000, v67
	v_cvt_pk_bf16_f32 v66, v66, v67
	ds_write_b32 v70, v66 offset:128
	v_mul_f32_e32 v66, v72, v82
	v_bfe_u32 v67, v66, 17, 1
	v_add3_u32 v66, v66, v67, s86
	v_mul_f32_e32 v67, v68, v83
	v_bfe_u32 v68, v67, 17, 1
	v_and_b32_e32 v66, 0xfffe0000, v66
	v_add3_u32 v67, v67, v68, s86
	v_and_b32_e32 v67, 0xfffe0000, v67
	v_cvt_pk_bf16_f32 v66, v66, v67
	ds_write_b32 v70, v66 offset:256
	v_mul_f32_e32 v66, v73, v82
	v_bfe_u32 v67, v66, 17, 1
	v_add3_u32 v66, v66, v67, s86
	v_mul_f32_e32 v67, v69, v83
	v_bfe_u32 v68, v67, 17, 1
	v_and_b32_e32 v66, 0xfffe0000, v66
	v_add3_u32 v67, v67, v68, s86
	v_and_b32_e32 v67, 0xfffe0000, v67
	v_cvt_pk_bf16_f32 v66, v66, v67
	ds_write_b32 v70, v66 offset:384
	v_mov_b32_e32 v66, 1.0
	s_and_b64 vcc, exec, s[4:5]
	v_mov_b32_e32 v68, 1.0
	v_mov_b32_e32 v69, 1.0
	s_cbranch_vccnz .LBB0_45
	v_mov_b32_e32 v68, v206
	v_mov_b32_e32 v69, v207
	s_nop 0
.LBB0_45:
	s_waitcnt vmcnt(0)
	v_mul_f32_e32 v62, v62, v68
	v_bfe_u32 v67, v62, 17, 1
	v_mul_f32_e32 v58, v58, v69
	v_add3_u32 v62, v62, v67, s86
	v_bfe_u32 v67, v58, 17, 1
	v_add3_u32 v58, v58, v67, s86
	v_and_b32_e32 v62, 0xfffe0000, v62
	v_and_b32_e32 v58, 0xfffe0000, v58
	v_cvt_pk_bf16_f32 v58, v62, v58
	v_add_u32_e32 v62, v142, v180
	ds_write_b32 v62, v58
	v_mul_f32_e32 v58, v63, v68
	v_bfe_u32 v63, v58, 17, 1
	v_mul_f32_e32 v59, v59, v69
	v_add3_u32 v58, v58, v63, s86
	v_bfe_u32 v63, v59, 17, 1
	v_and_b32_e32 v58, 0xfffe0000, v58
	v_add3_u32 v59, v59, v63, s86
	v_and_b32_e32 v59, 0xfffe0000, v59
	v_cvt_pk_bf16_f32 v58, v58, v59
	ds_write_b32 v62, v58 offset:128
	v_mul_f32_e32 v58, v64, v68
	v_bfe_u32 v59, v58, 17, 1
	v_add3_u32 v58, v58, v59, s86
	v_mul_f32_e32 v59, v60, v69
	v_bfe_u32 v60, v59, 17, 1
	v_and_b32_e32 v58, 0xfffe0000, v58
	v_add3_u32 v59, v59, v60, s86
	v_and_b32_e32 v59, 0xfffe0000, v59
	v_cvt_pk_bf16_f32 v58, v58, v59
	ds_write_b32 v62, v58 offset:256
	v_mul_f32_e32 v58, v65, v68
	v_bfe_u32 v59, v58, 17, 1
	v_add3_u32 v58, v58, v59, s86
	v_mul_f32_e32 v59, v61, v69
	v_bfe_u32 v60, v59, 17, 1
	v_and_b32_e32 v58, 0xfffe0000, v58
	v_add3_u32 v59, v59, v60, s86
	s_and_b64 vcc, exec, s[4:5]
	v_mov_b32_e32 v67, 1.0
	v_and_b32_e32 v59, 0xfffe0000, v59
	v_cvt_pk_bf16_f32 v58, v58, v59
	ds_write_b32 v62, v58 offset:384
	s_cbranch_vccnz .LBB0_47
	v_mov_b32_e32 v66, v208
	v_mov_b32_e32 v67, v209
	s_nop 0
.LBB0_47:
	s_waitcnt vmcnt(0)
	v_mul_f32_e32 v54, v54, v66
	v_bfe_u32 v58, v54, 17, 1
	v_mul_f32_e32 v50, v50, v67
	v_add3_u32 v54, v54, v58, s86
	v_bfe_u32 v58, v50, 17, 1
	v_add3_u32 v50, v50, v58, s86
	v_and_b32_e32 v54, 0xfffe0000, v54
	v_and_b32_e32 v50, 0xfffe0000, v50
	v_cvt_pk_bf16_f32 v50, v54, v50
	v_add_u32_e32 v54, v142, v182
	ds_write_b32 v54, v50
	v_mul_f32_e32 v50, v55, v66
	v_bfe_u32 v55, v50, 17, 1
	v_mul_f32_e32 v51, v51, v67
	v_add3_u32 v50, v50, v55, s86
	v_bfe_u32 v55, v51, 17, 1
	v_and_b32_e32 v50, 0xfffe0000, v50
	v_add3_u32 v51, v51, v55, s86
	v_and_b32_e32 v51, 0xfffe0000, v51
	v_cvt_pk_bf16_f32 v50, v50, v51
	ds_write_b32 v54, v50 offset:128
	v_mul_f32_e32 v50, v56, v66
	v_bfe_u32 v51, v50, 17, 1
	v_add3_u32 v50, v50, v51, s86
	v_mul_f32_e32 v51, v52, v67
	v_bfe_u32 v52, v51, 17, 1
	v_and_b32_e32 v50, 0xfffe0000, v50
	v_add3_u32 v51, v51, v52, s86
	v_and_b32_e32 v51, 0xfffe0000, v51
	v_cvt_pk_bf16_f32 v50, v50, v51
	ds_write_b32 v54, v50 offset:256
	v_mul_f32_e32 v50, v57, v66
	v_bfe_u32 v51, v50, 17, 1
	v_add3_u32 v50, v50, v51, s86
	v_mul_f32_e32 v51, v53, v67
	v_bfe_u32 v52, v51, 17, 1
	v_and_b32_e32 v50, 0xfffe0000, v50
	v_add3_u32 v51, v51, v52, s86
	v_and_b32_e32 v51, 0xfffe0000, v51
	v_cvt_pk_bf16_f32 v50, v50, v51
	ds_write_b32 v54, v50 offset:384
	v_mov_b32_e32 v50, 1.0
	s_and_b64 vcc, exec, s[4:5]
	v_mov_b32_e32 v52, 1.0
	v_mov_b32_e32 v53, 1.0
	s_cbranch_vccnz .LBB0_49
	v_mov_b32_e32 v52, v210
	v_mov_b32_e32 v53, v211
	s_nop 0
.LBB0_49:
	s_waitcnt vmcnt(0)
	v_mul_f32_e32 v46, v46, v52
	v_bfe_u32 v51, v46, 17, 1
	v_mul_f32_e32 v42, v42, v53
	v_add3_u32 v46, v46, v51, s86
	v_bfe_u32 v51, v42, 17, 1
	v_add3_u32 v42, v42, v51, s86
	v_and_b32_e32 v46, 0xfffe0000, v46
	v_and_b32_e32 v42, 0xfffe0000, v42
	v_cvt_pk_bf16_f32 v42, v46, v42
	v_add_u32_e32 v46, v142, v184
	ds_write_b32 v46, v42
	v_mul_f32_e32 v42, v47, v52
	v_bfe_u32 v47, v42, 17, 1
	v_mul_f32_e32 v43, v43, v53
	v_add3_u32 v42, v42, v47, s86
	v_bfe_u32 v47, v43, 17, 1
	v_and_b32_e32 v42, 0xfffe0000, v42
	v_add3_u32 v43, v43, v47, s86
	v_and_b32_e32 v43, 0xfffe0000, v43
	v_cvt_pk_bf16_f32 v42, v42, v43
	ds_write_b32 v46, v42 offset:128
	v_mul_f32_e32 v42, v48, v52
	v_bfe_u32 v43, v42, 17, 1
	v_add3_u32 v42, v42, v43, s86
	v_mul_f32_e32 v43, v44, v53
	v_bfe_u32 v44, v43, 17, 1
	v_and_b32_e32 v42, 0xfffe0000, v42
	v_add3_u32 v43, v43, v44, s86
	v_and_b32_e32 v43, 0xfffe0000, v43
	v_cvt_pk_bf16_f32 v42, v42, v43
	ds_write_b32 v46, v42 offset:256
	v_mul_f32_e32 v42, v49, v52
	v_bfe_u32 v43, v42, 17, 1
	v_add3_u32 v42, v42, v43, s86
	v_mul_f32_e32 v43, v45, v53
	v_bfe_u32 v44, v43, 17, 1
	v_and_b32_e32 v42, 0xfffe0000, v42
	v_add3_u32 v43, v43, v44, s86
	s_and_b64 vcc, exec, s[4:5]
	v_mov_b32_e32 v51, 1.0
	v_and_b32_e32 v43, 0xfffe0000, v43
	v_cvt_pk_bf16_f32 v42, v42, v43
	ds_write_b32 v46, v42 offset:384
	s_cbranch_vccnz .LBB0_51
	v_mov_b32_e32 v50, v212
	v_mov_b32_e32 v51, v213
	s_nop 0
.LBB0_51:
	s_waitcnt vmcnt(0)
	v_mul_f32_e32 v38, v38, v50
	v_bfe_u32 v42, v38, 17, 1
	v_mul_f32_e32 v34, v34, v51
	v_add3_u32 v38, v38, v42, s86
	v_bfe_u32 v42, v34, 17, 1
	v_add3_u32 v34, v34, v42, s86
	v_and_b32_e32 v38, 0xfffe0000, v38
	v_and_b32_e32 v34, 0xfffe0000, v34
	v_cvt_pk_bf16_f32 v34, v38, v34
	v_add_u32_e32 v38, v142, v186
	ds_write_b32 v38, v34
	v_mul_f32_e32 v34, v39, v50
	v_bfe_u32 v39, v34, 17, 1
	v_mul_f32_e32 v35, v35, v51
	v_add3_u32 v34, v34, v39, s86
	v_bfe_u32 v39, v35, 17, 1
	v_and_b32_e32 v34, 0xfffe0000, v34
	v_add3_u32 v35, v35, v39, s86
	v_and_b32_e32 v35, 0xfffe0000, v35
	v_cvt_pk_bf16_f32 v34, v34, v35
	ds_write_b32 v38, v34 offset:128
	v_mul_f32_e32 v34, v40, v50
	v_bfe_u32 v35, v34, 17, 1
	v_add3_u32 v34, v34, v35, s86
	v_mul_f32_e32 v35, v36, v51
	v_bfe_u32 v36, v35, 17, 1
	v_and_b32_e32 v34, 0xfffe0000, v34
	v_add3_u32 v35, v35, v36, s86
	v_and_b32_e32 v35, 0xfffe0000, v35
	v_cvt_pk_bf16_f32 v34, v34, v35
	ds_write_b32 v38, v34 offset:256
	v_mul_f32_e32 v34, v41, v50
	v_bfe_u32 v35, v34, 17, 1
	v_add3_u32 v34, v34, v35, s86
	v_mul_f32_e32 v35, v37, v51
	v_bfe_u32 v36, v35, 17, 1
	v_and_b32_e32 v34, 0xfffe0000, v34
	v_add3_u32 v35, v35, v36, s86
	v_and_b32_e32 v35, 0xfffe0000, v35
	v_cvt_pk_bf16_f32 v34, v34, v35
	ds_write_b32 v38, v34 offset:384
	v_mov_b32_e32 v34, 1.0
	s_and_b64 vcc, exec, s[4:5]
	v_mov_b32_e32 v36, 1.0
	v_mov_b32_e32 v37, 1.0
	s_cbranch_vccnz .LBB0_53
	v_mov_b32_e32 v36, v214
	v_mov_b32_e32 v37, v215
	s_nop 0
.LBB0_53:
	s_waitcnt vmcnt(0)
	v_mul_f32_e32 v30, v30, v36
	v_bfe_u32 v35, v30, 17, 1
	v_mul_f32_e32 v26, v26, v37
	v_add3_u32 v30, v30, v35, s86
	v_bfe_u32 v35, v26, 17, 1
	v_add3_u32 v26, v26, v35, s86
	v_and_b32_e32 v26, 0xfffe0000, v26
	v_and_b32_e32 v30, 0xfffe0000, v30
	v_cvt_pk_bf16_f32 v26, v30, v26
	ds_write_b32 v38, v26 offset:1032
	v_mul_f32_e32 v26, v31, v36
	v_bfe_u32 v30, v26, 17, 1
	v_mul_f32_e32 v27, v27, v37
	v_add3_u32 v26, v26, v30, s86
	v_bfe_u32 v30, v27, 17, 1
	v_and_b32_e32 v26, 0xfffe0000, v26
	v_add3_u32 v27, v27, v30, s86
	v_and_b32_e32 v27, 0xfffe0000, v27
	v_cvt_pk_bf16_f32 v26, v26, v27
	ds_write_b32 v38, v26 offset:1160
	v_mul_f32_e32 v26, v32, v36
	v_bfe_u32 v27, v26, 17, 1
	v_add3_u32 v26, v26, v27, s86
	v_mul_f32_e32 v27, v28, v37
	v_bfe_u32 v28, v27, 17, 1
	v_and_b32_e32 v26, 0xfffe0000, v26
	v_add3_u32 v27, v27, v28, s86
	v_and_b32_e32 v27, 0xfffe0000, v27
	v_cvt_pk_bf16_f32 v26, v26, v27
	ds_write_b32 v38, v26 offset:1288
	v_mul_f32_e32 v26, v33, v36
	v_bfe_u32 v27, v26, 17, 1
	v_add3_u32 v26, v26, v27, s86
	v_mul_f32_e32 v27, v29, v37
	v_bfe_u32 v28, v27, 17, 1
	v_and_b32_e32 v26, 0xfffe0000, v26
	v_add3_u32 v27, v27, v28, s86
	s_and_b64 vcc, exec, s[4:5]
	v_mov_b32_e32 v35, 1.0
	v_and_b32_e32 v27, 0xfffe0000, v27
	v_cvt_pk_bf16_f32 v26, v26, v27
	ds_write_b32 v38, v26 offset:1416
	s_cbranch_vccnz .LBB0_55
	v_mov_b32_e32 v34, v216
	v_mov_b32_e32 v35, v217
	s_nop 0
.LBB0_55:
	s_waitcnt vmcnt(0)
	v_mul_f32_e32 v22, v22, v34
	v_bfe_u32 v26, v22, 17, 1
	v_mul_f32_e32 v18, v18, v35
	v_add3_u32 v22, v22, v26, s86
	v_bfe_u32 v26, v18, 17, 1
	v_add3_u32 v18, v18, v26, s86
	v_and_b32_e32 v18, 0xfffe0000, v18
	v_and_b32_e32 v22, 0xfffe0000, v22
	v_cvt_pk_bf16_f32 v18, v22, v18
	ds_write_b32 v38, v18 offset:2064
	v_mul_f32_e32 v18, v23, v34
	v_bfe_u32 v22, v18, 17, 1
	v_mul_f32_e32 v19, v19, v35
	v_add3_u32 v18, v18, v22, s86
	v_bfe_u32 v22, v19, 17, 1
	v_and_b32_e32 v18, 0xfffe0000, v18
	v_add3_u32 v19, v19, v22, s86
	v_and_b32_e32 v19, 0xfffe0000, v19
	v_cvt_pk_bf16_f32 v18, v18, v19
	ds_write_b32 v38, v18 offset:2192
	v_mul_f32_e32 v18, v24, v34
	v_bfe_u32 v19, v18, 17, 1
	v_add3_u32 v18, v18, v19, s86
	v_mul_f32_e32 v19, v20, v35
	v_bfe_u32 v20, v19, 17, 1
	v_and_b32_e32 v18, 0xfffe0000, v18
	v_add3_u32 v19, v19, v20, s86
	v_and_b32_e32 v19, 0xfffe0000, v19
	v_cvt_pk_bf16_f32 v18, v18, v19
	ds_write_b32 v38, v18 offset:2320
	v_mul_f32_e32 v18, v25, v34
	v_bfe_u32 v19, v18, 17, 1
	v_add3_u32 v18, v18, v19, s86
	v_mul_f32_e32 v19, v21, v35
	v_bfe_u32 v20, v19, 17, 1
	v_and_b32_e32 v18, 0xfffe0000, v18
	v_add3_u32 v19, v19, v20, s86
	v_and_b32_e32 v19, 0xfffe0000, v19
	v_cvt_pk_bf16_f32 v18, v18, v19
	ds_write_b32 v38, v18 offset:2448
	v_mov_b32_e32 v18, 1.0
	s_and_b64 vcc, exec, s[4:5]
	v_mov_b32_e32 v20, 1.0
	v_mov_b32_e32 v21, 1.0
	s_cbranch_vccnz .LBB0_57
	v_mov_b32_e32 v20, v218
	v_mov_b32_e32 v21, v219
	s_nop 0
.LBB0_57:
	s_waitcnt vmcnt(0)
	v_mul_f32_e32 v14, v14, v20
	v_bfe_u32 v19, v14, 17, 1
	v_mul_f32_e32 v10, v10, v21
	v_add3_u32 v14, v14, v19, s86
	v_bfe_u32 v19, v10, 17, 1
	v_add3_u32 v10, v10, v19, s86
	v_and_b32_e32 v10, 0xfffe0000, v10
	v_and_b32_e32 v14, 0xfffe0000, v14
	v_cvt_pk_bf16_f32 v10, v14, v10
	ds_write_b32 v38, v10 offset:3096
	v_mul_f32_e32 v10, v15, v20
	v_bfe_u32 v14, v10, 17, 1
	v_mul_f32_e32 v11, v11, v21
	v_add3_u32 v10, v10, v14, s86
	v_bfe_u32 v14, v11, 17, 1
	v_and_b32_e32 v10, 0xfffe0000, v10
	v_add3_u32 v11, v11, v14, s86
	v_and_b32_e32 v11, 0xfffe0000, v11
	v_cvt_pk_bf16_f32 v10, v10, v11
	ds_write_b32 v38, v10 offset:3224
	v_mul_f32_e32 v10, v16, v20
	v_bfe_u32 v11, v10, 17, 1
	v_add3_u32 v10, v10, v11, s86
	v_mul_f32_e32 v11, v12, v21
	v_bfe_u32 v12, v11, 17, 1
	v_and_b32_e32 v10, 0xfffe0000, v10
	v_add3_u32 v11, v11, v12, s86
	v_and_b32_e32 v11, 0xfffe0000, v11
	v_cvt_pk_bf16_f32 v10, v10, v11
	ds_write_b32 v38, v10 offset:3352
	v_mul_f32_e32 v10, v17, v20
	v_bfe_u32 v11, v10, 17, 1
	v_add3_u32 v10, v10, v11, s86
	v_mul_f32_e32 v11, v13, v21
	v_bfe_u32 v12, v11, 17, 1
	v_and_b32_e32 v10, 0xfffe0000, v10
	v_add3_u32 v11, v11, v12, s86
	s_and_b64 vcc, exec, s[4:5]
	v_mov_b32_e32 v19, 1.0
	v_and_b32_e32 v11, 0xfffe0000, v11
	v_cvt_pk_bf16_f32 v10, v10, v11
	ds_write_b32 v38, v10 offset:3480
	s_cbranch_vccnz .LBB0_59
	v_mov_b32_e32 v18, v230
	v_mov_b32_e32 v19, v231
	s_nop 0

.LBB0_61:
	s_andn2_b64 vcc, exec, s[4:5]
	s_cbranch_vccnz .LBB0_95
	s_mul_i32 s4, s42, 0x5800000
	s_mul_hi_i32 s2, s42, 0x5800000
	s_add_u32 s4, s20, s4
	s_addc_u32 s5, s21, s2
	s_lshl_b32 s44, s42, 11
	s_ashr_i32 s45, s44, 31
	s_lshl_b64 s[44:45], s[44:45], 2
	s_add_u32 s44, s18, s44
	s_addc_u32 s45, s19, s45
	s_add_i32 s2, s70, 0xf500
	s_and_b32 s38, s2, 0xffff
	s_mul_i32 s38, s38, 0xba2f
	s_lshr_b32 s43, s38, 22
	s_mul_i32 s71, s43, 0x58
	s_lshr_b32 s38, s38, 16
	s_sub_i32 vcc_lo, s2, s71
	s_and_b32 s2, vcc_lo, 0xffff
	s_and_b32 s71, s38, 0xffc0
	s_bitcmp0_b32 vcc_lo, 0
	s_cselect_b32 s38, 0, 0x1600
	s_lshl_b32 vcc_lo, s2, 6
	s_and_b32 vcc_lo, vcc_lo, 0x1f80
	s_add_i32 s38, s38, vcc_lo
	v_or_b32_e32 v137, s71, v165
	v_mov_b64_e32 v[2:3], s[4:5]
	v_mad_u64_u32 v[2:3], s[4:5], v137, s88, v[2:3]
	s_lshl_b32 s38, s38, 2
	v_lshl_add_u64 v[2:3], v[2:3], 0, s[38:39]
	v_lshlrev_b32_e32 v132, 2, v130
	v_lshl_add_u64 v[2:3], v[2:3], 0, v[132:133]
	v_add_co_u32_e32 v4, vcc, s88, v2
	v_cndmask_b32_e64 v132, 0, 1, s[34:35]
	s_nop 0
	v_addc_co_u32_e32 v5, vcc, 0, v3, vcc
	global_load_dwordx4 v[126:129], v[2:3], off
	global_load_dwordx4 v[122:125], v[4:5], off
	v_add_co_u32_e32 v4, vcc, s89, v2
	v_mov_b32_e32 v136, 1.0
	s_nop 0
	v_addc_co_u32_e32 v5, vcc, 0, v3, vcc
	v_add_co_u32_e32 v6, vcc, s90, v2
	v_cmp_ne_u32_e64 s[4:5], 1, v132
	s_nop 0
	v_addc_co_u32_e32 v7, vcc, 0, v3, vcc
	global_load_dwordx4 v[118:121], v[4:5], off
	global_load_dwordx4 v[114:117], v[6:7], off
	v_add_co_u32_e32 v4, vcc, s76, v2
	v_mov_b32_e32 v138, 1.0
	s_nop 0
	v_addc_co_u32_e32 v5, vcc, 0, v3, vcc
	v_add_co_u32_e32 v6, vcc, s91, v2
	v_mov_b32_e32 v139, 1.0
	s_nop 0
	v_addc_co_u32_e32 v7, vcc, 0, v3, vcc
	global_load_dwordx4 v[110:113], v[4:5], off
	global_load_dwordx4 v[106:109], v[6:7], off
	v_add_co_u32_e32 v4, vcc, s92, v2
	s_nop 1
	v_addc_co_u32_e32 v5, vcc, 0, v3, vcc
	v_add_co_u32_e32 v6, vcc, s87, v2
	s_nop 1
	v_addc_co_u32_e32 v7, vcc, 0, v3, vcc
	global_load_dwordx4 v[102:105], v[4:5], off
	global_load_dwordx4 v[98:101], v[6:7], off
	v_add_co_u32_e32 v4, vcc, s93, v2
	s_nop 1
	v_addc_co_u32_e32 v5, vcc, 0, v3, vcc
	v_add_co_u32_e32 v6, vcc, s94, v2
	s_nop 1
	v_addc_co_u32_e32 v7, vcc, 0, v3, vcc
	global_load_dwordx4 v[94:97], v[4:5], off
	global_load_dwordx4 v[90:93], v[6:7], off
	v_add_co_u32_e32 v4, vcc, s95, v2
	s_nop 1
	v_addc_co_u32_e32 v5, vcc, 0, v3, vcc
	v_add_co_u32_e32 v6, vcc, s96, v2
	s_nop 1
	v_addc_co_u32_e32 v7, vcc, 0, v3, vcc
	global_load_dwordx4 v[86:89], v[4:5], off
	global_load_dwordx4 v[82:85], v[6:7], off
	v_add_co_u32_e32 v4, vcc, s97, v2
	s_nop 1
	v_addc_co_u32_e32 v5, vcc, 0, v3, vcc
	v_add_co_u32_e32 v6, vcc, s98, v2
	s_nop 1
	v_addc_co_u32_e32 v7, vcc, 0, v3, vcc
	global_load_dwordx4 v[78:81], v[4:5], off
	global_load_dwordx4 v[74:77], v[6:7], off
	v_add_co_u32_e32 v4, vcc, s99, v2
	s_nop 1
	v_addc_co_u32_e32 v5, vcc, 0, v3, vcc
	v_add_co_u32_e32 v6, vcc, s48, v2
	s_nop 1
	v_addc_co_u32_e32 v7, vcc, 0, v3, vcc
	global_load_dwordx4 v[70:73], v[4:5], off
	global_load_dwordx4 v[66:69], v[6:7], off
	v_add_co_u32_e32 v4, vcc, s49, v2
	s_nop 1
	v_addc_co_u32_e32 v5, vcc, 0, v3, vcc
	v_add_co_u32_e32 v6, vcc, s50, v2
	s_nop 1
	v_addc_co_u32_e32 v7, vcc, 0, v3, vcc
	global_load_dwordx4 v[62:65], v[4:5], off
	global_load_dwordx4 v[58:61], v[6:7], off
	v_add_co_u32_e32 v4, vcc, s51, v2
	s_nop 1
	v_addc_co_u32_e32 v5, vcc, 0, v3, vcc
	v_add_co_u32_e32 v6, vcc, s52, v2
	s_nop 1
	v_addc_co_u32_e32 v7, vcc, 0, v3, vcc
	global_load_dwordx4 v[54:57], v[4:5], off
	global_load_dwordx4 v[50:53], v[6:7], off
	v_add_co_u32_e32 v4, vcc, s53, v2
	s_nop 1
	v_addc_co_u32_e32 v5, vcc, 0, v3, vcc
	v_add_co_u32_e32 v6, vcc, s54, v2
	s_nop 1
	v_addc_co_u32_e32 v7, vcc, 0, v3, vcc
	global_load_dwordx4 v[46:49], v[4:5], off
	global_load_dwordx4 v[42:45], v[6:7], off
	v_add_co_u32_e32 v4, vcc, s55, v2
	s_nop 1
	v_addc_co_u32_e32 v5, vcc, 0, v3, vcc
	v_add_co_u32_e32 v6, vcc, s56, v2
	s_nop 1
	v_addc_co_u32_e32 v7, vcc, 0, v3, vcc
	global_load_dwordx4 v[38:41], v[4:5], off
	global_load_dwordx4 v[34:37], v[6:7], off
	v_add_co_u32_e32 v4, vcc, s57, v2
	s_nop 1
	v_addc_co_u32_e32 v5, vcc, 0, v3, vcc
	v_add_co_u32_e32 v6, vcc, s59, v2
	s_nop 1
	v_addc_co_u32_e32 v7, vcc, 0, v3, vcc
	global_load_dwordx4 v[30:33], v[4:5], off
	global_load_dwordx4 v[26:29], v[6:7], off
	v_add_co_u32_e32 v4, vcc, s60, v2
	s_nop 1
	v_addc_co_u32_e32 v5, vcc, 0, v3, vcc
	v_add_co_u32_e32 v6, vcc, s62, v2
	s_nop 1
	v_addc_co_u32_e32 v7, vcc, 0, v3, vcc
	global_load_dwordx4 v[22:25], v[4:5], off
	global_load_dwordx4 v[18:21], v[6:7], off
	v_add_co_u32_e32 v4, vcc, s63, v2
	s_nop 1
	v_addc_co_u32_e32 v5, vcc, 0, v3, vcc
	v_add_co_u32_e32 v6, vcc, 0x273000, v2
	s_nop 1
	v_addc_co_u32_e32 v7, vcc, 0, v3, vcc
	global_load_dwordx4 v[14:17], v[4:5], off
	global_load_dwordx4 v[10:13], v[6:7], off
	v_add_co_u32_e32 v4, vcc, 0x294000, v2
	s_nop 1
	v_addc_co_u32_e32 v5, vcc, 0, v3, vcc
	v_add_co_u32_e32 v2, vcc, 0x29f000, v2
	s_nop 1
	v_addc_co_u32_e32 v3, vcc, 0, v3, vcc
	global_load_dwordx4 v[6:9], v[4:5], off
	s_nop 0
	global_load_dwordx4 v[2:5], v[2:3], off
	s_andn2_b64 vcc, exec, s[34:35]
	s_cbranch_vccnz .LBB0_64
	v_lshlrev_b32_e32 v132, 2, v137
	global_load_dwordx2 v[138:139], v132, s[44:45]
	v_or_b32_e32 v228, s71, v166
	v_lshlrev_b32_e32 v228, 2, v228
	global_load_dwordx2 v[192:193], v228, s[44:45]
	v_or_b32_e32 v228, s71, v167
	v_lshlrev_b32_e32 v228, 2, v228
	global_load_dwordx2 v[194:195], v228, s[44:45]
	v_or_b32_e32 v228, s71, v169
	v_lshlrev_b32_e32 v228, 2, v228
	global_load_dwordx2 v[196:197], v228, s[44:45]
	v_or_b32_e32 v228, s71, v171
	v_lshlrev_b32_e32 v228, 2, v228
	global_load_dwordx2 v[198:199], v228, s[44:45]
	v_or_b32_e32 v228, s71, v173
	v_lshlrev_b32_e32 v228, 2, v228
	global_load_dwordx2 v[200:201], v228, s[44:45]
	v_or_b32_e32 v228, s71, v175
	v_lshlrev_b32_e32 v228, 2, v228
	global_load_dwordx2 v[202:203], v228, s[44:45]
	v_or_b32_e32 v228, s71, v177
	v_lshlrev_b32_e32 v228, 2, v228
	global_load_dwordx2 v[204:205], v228, s[44:45]
	v_or_b32_e32 v228, s71, v179
	v_lshlrev_b32_e32 v228, 2, v228
	global_load_dwordx2 v[206:207], v228, s[44:45]
	v_or_b32_e32 v228, s71, v181
	v_lshlrev_b32_e32 v228, 2, v228
	global_load_dwordx2 v[208:209], v228, s[44:45]
	v_or_b32_e32 v228, s71, v183
	v_lshlrev_b32_e32 v228, 2, v228
	global_load_dwordx2 v[210:211], v228, s[44:45]
	v_or_b32_e32 v228, s71, v185
	v_lshlrev_b32_e32 v228, 2, v228
	global_load_dwordx2 v[212:213], v228, s[44:45]
	v_or_b32_e32 v228, s71, v187
	v_lshlrev_b32_e32 v228, 2, v228
	global_load_dwordx2 v[214:215], v228, s[44:45]
	v_or_b32_e32 v228, s71, v188
	v_lshlrev_b32_e32 v228, 2, v228
	global_load_dwordx2 v[216:217], v228, s[44:45]
	v_or_b32_e32 v228, s71, v189
	v_lshlrev_b32_e32 v228, 2, v228
	global_load_dwordx2 v[218:219], v228, s[44:45]
	v_or_b32_e32 v228, s71, v190
	v_lshlrev_b32_e32 v228, 2, v228
	global_load_dwordx2 v[230:231], v228, s[44:45]

.LBB0_96:
	s_andn2_b64 vcc, exec, s[4:5]
	s_cbranch_vccnz .LBB0_13
	s_mul_i32 s4, s42, 0x5800000
	s_mul_hi_i32 s2, s42, 0x5800000
	s_add_u32 s4, s14, s4
	s_addc_u32 s5, s15, s2
	s_lshl_b32 s42, s42, 11
	s_ashr_i32 s43, s42, 31
	s_lshl_b64 s[42:43], s[42:43], 2
	s_add_u32 s42, s12, s42
	s_mul_i32 s2, s70, 0xba3
	s_addc_u32 s43, s13, s43
	s_lshr_b32 s38, s2, 31
	s_ashr_i32 s2, s2, 18
	s_add_i32 s38, s2, s38
	s_mul_i32 s2, s38, 0x58
	s_sub_i32 s2, s70, s2
	s_lshl_b32 s45, s38, 6
	s_sext_i32_i16 s44, s2
	s_bitcmp0_b32 s2, 0
	s_cselect_b32 s2, 0, 0x1600
	s_lshl_b32 s70, s44, 6
	s_and_b32 s70, s70, 0xffffff80
	v_or_b32_e32 v136, s45, v165
	s_add_i32 s70, s2, s70
	v_mul_hi_i32_i24_e32 v3, 0xb000, v136
	v_mul_i32_i24_e32 v2, 0xb000, v136
	v_lshl_add_u64 v[2:3], s[4:5], 0, v[2:3]
	s_ashr_i32 s71, s70, 31
	v_lshl_add_u64 v[2:3], s[70:71], 2, v[2:3]
	v_lshlrev_b32_e32 v132, 2, v130
	v_lshl_add_u64 v[2:3], v[2:3], 0, v[132:133]
	v_add_co_u32_e32 v4, vcc, s88, v2
	v_cndmask_b32_e64 v132, 0, 1, s[36:37]
	s_nop 0
	v_addc_co_u32_e32 v5, vcc, 0, v3, vcc
	global_load_dwordx4 v[126:129], v[2:3], off
	global_load_dwordx4 v[122:125], v[4:5], off
	v_add_co_u32_e32 v4, vcc, s89, v2
	v_mov_b32_e32 v138, 1.0
	s_nop 0
	v_addc_co_u32_e32 v5, vcc, 0, v3, vcc
	v_add_co_u32_e32 v6, vcc, s90, v2
	v_cmp_ne_u32_e64 s[4:5], 1, v132
	s_nop 0
	v_addc_co_u32_e32 v7, vcc, 0, v3, vcc
	global_load_dwordx4 v[118:121], v[4:5], off
	global_load_dwordx4 v[114:117], v[6:7], off
	v_add_co_u32_e32 v4, vcc, s76, v2
	v_mov_b32_e32 v140, 1.0
	s_nop 0
	v_addc_co_u32_e32 v5, vcc, 0, v3, vcc
	v_add_co_u32_e32 v6, vcc, s91, v2
	v_mov_b32_e32 v141, 1.0
	s_nop 0
	v_addc_co_u32_e32 v7, vcc, 0, v3, vcc
	global_load_dwordx4 v[110:113], v[4:5], off
	global_load_dwordx4 v[106:109], v[6:7], off
	v_add_co_u32_e32 v4, vcc, s92, v2
	s_nop 1
	v_addc_co_u32_e32 v5, vcc, 0, v3, vcc
	v_add_co_u32_e32 v6, vcc, s87, v2
	s_nop 1
	v_addc_co_u32_e32 v7, vcc, 0, v3, vcc
	global_load_dwordx4 v[102:105], v[4:5], off
	global_load_dwordx4 v[98:101], v[6:7], off
	v_add_co_u32_e32 v4, vcc, s93, v2
	s_nop 1
	v_addc_co_u32_e32 v5, vcc, 0, v3, vcc
	v_add_co_u32_e32 v6, vcc, s94, v2
	s_nop 1
	v_addc_co_u32_e32 v7, vcc, 0, v3, vcc
	global_load_dwordx4 v[94:97], v[4:5], off
	global_load_dwordx4 v[90:93], v[6:7], off
	v_add_co_u32_e32 v4, vcc, s95, v2
	s_nop 1
	v_addc_co_u32_e32 v5, vcc, 0, v3, vcc
	v_add_co_u32_e32 v6, vcc, s96, v2
	s_nop 1
	v_addc_co_u32_e32 v7, vcc, 0, v3, vcc
	global_load_dwordx4 v[86:89], v[4:5], off
	global_load_dwordx4 v[82:85], v[6:7], off
	v_add_co_u32_e32 v4, vcc, s97, v2
	s_nop 1
	v_addc_co_u32_e32 v5, vcc, 0, v3, vcc
	v_add_co_u32_e32 v6, vcc, s98, v2
	s_nop 1
	v_addc_co_u32_e32 v7, vcc, 0, v3, vcc
	global_load_dwordx4 v[78:81], v[4:5], off
	global_load_dwordx4 v[74:77], v[6:7], off
	v_add_co_u32_e32 v4, vcc, s99, v2
	s_nop 1
	v_addc_co_u32_e32 v5, vcc, 0, v3, vcc
	v_add_co_u32_e32 v6, vcc, s48, v2
	s_nop 1
	v_addc_co_u32_e32 v7, vcc, 0, v3, vcc
	global_load_dwordx4 v[70:73], v[4:5], off
	global_load_dwordx4 v[66:69], v[6:7], off
	v_add_co_u32_e32 v4, vcc, s49, v2
	s_nop 1
	v_addc_co_u32_e32 v5, vcc, 0, v3, vcc
	v_add_co_u32_e32 v6, vcc, s50, v2
	s_nop 1
	v_addc_co_u32_e32 v7, vcc, 0, v3, vcc
	global_load_dwordx4 v[62:65], v[4:5], off
	global_load_dwordx4 v[58:61], v[6:7], off
	v_add_co_u32_e32 v4, vcc, s51, v2
	s_nop 1
	v_addc_co_u32_e32 v5, vcc, 0, v3, vcc
	v_add_co_u32_e32 v6, vcc, s52, v2
	s_nop 1
	v_addc_co_u32_e32 v7, vcc, 0, v3, vcc
	global_load_dwordx4 v[54:57], v[4:5], off
	global_load_dwordx4 v[50:53], v[6:7], off
	v_add_co_u32_e32 v4, vcc, s53, v2
	s_nop 1
	v_addc_co_u32_e32 v5, vcc, 0, v3, vcc
	v_add_co_u32_e32 v6, vcc, s54, v2
	s_nop 1
	v_addc_co_u32_e32 v7, vcc, 0, v3, vcc
	global_load_dwordx4 v[46:49], v[4:5], off
	global_load_dwordx4 v[42:45], v[6:7], off
	v_add_co_u32_e32 v4, vcc, s55, v2
	s_nop 1
	v_addc_co_u32_e32 v5, vcc, 0, v3, vcc
	v_add_co_u32_e32 v6, vcc, s56, v2
	s_nop 1
	v_addc_co_u32_e32 v7, vcc, 0, v3, vcc
	global_load_dwordx4 v[38:41], v[4:5], off
	global_load_dwordx4 v[34:37], v[6:7], off
	v_add_co_u32_e32 v4, vcc, s57, v2
	s_nop 1
	v_addc_co_u32_e32 v5, vcc, 0, v3, vcc
	v_add_co_u32_e32 v6, vcc, s59, v2
	s_nop 1
	v_addc_co_u32_e32 v7, vcc, 0, v3, vcc
	global_load_dwordx4 v[30:33], v[4:5], off
	global_load_dwordx4 v[26:29], v[6:7], off
	v_add_co_u32_e32 v4, vcc, s60, v2
	s_nop 1
	v_addc_co_u32_e32 v5, vcc, 0, v3, vcc
	v_add_co_u32_e32 v6, vcc, s62, v2
	s_nop 1
	v_addc_co_u32_e32 v7, vcc, 0, v3, vcc
	global_load_dwordx4 v[22:25], v[4:5], off
	global_load_dwordx4 v[18:21], v[6:7], off
	v_add_co_u32_e32 v4, vcc, s63, v2
	s_nop 1
	v_addc_co_u32_e32 v5, vcc, 0, v3, vcc
	v_add_co_u32_e32 v6, vcc, 0x273000, v2
	s_nop 1
	v_addc_co_u32_e32 v7, vcc, 0, v3, vcc
	global_load_dwordx4 v[14:17], v[4:5], off
	global_load_dwordx4 v[10:13], v[6:7], off
	v_add_co_u32_e32 v4, vcc, 0x294000, v2
	s_nop 1
	v_addc_co_u32_e32 v5, vcc, 0, v3, vcc
	v_add_co_u32_e32 v2, vcc, 0x29f000, v2
	s_nop 1
	v_addc_co_u32_e32 v3, vcc, 0, v3, vcc
	global_load_dwordx4 v[6:9], v[4:5], off
	s_nop 0
	global_load_dwordx4 v[2:5], v[2:3], off
	s_andn2_b64 vcc, exec, s[36:37]
	s_cbranch_vccnz .LBB0_99
	v_ashrrev_i32_e32 v137, 31, v136
	v_lshl_add_u64 v[136:137], v[136:137], 2, s[42:43]
	global_load_dwordx2 v[140:141], v[136:137], off
	v_or_b32_e32 v228, s45, v166
	v_ashrrev_i32_e32 v229, 31, v228
	v_lshl_add_u64 v[228:229], v[228:229], 2, s[42:43]
	global_load_dwordx2 v[192:193], v[228:229], off
	v_or_b32_e32 v228, s45, v167
	v_ashrrev_i32_e32 v229, 31, v228
	v_lshl_add_u64 v[228:229], v[228:229], 2, s[42:43]
	global_load_dwordx2 v[194:195], v[228:229], off
	v_or_b32_e32 v228, s45, v169
	v_ashrrev_i32_e32 v229, 31, v228
	v_lshl_add_u64 v[228:229], v[228:229], 2, s[42:43]
	global_load_dwordx2 v[196:197], v[228:229], off
	v_or_b32_e32 v228, s45, v171
	v_ashrrev_i32_e32 v229, 31, v228
	v_lshl_add_u64 v[228:229], v[228:229], 2, s[42:43]
	global_load_dwordx2 v[198:199], v[228:229], off
	v_or_b32_e32 v228, s45, v173
	v_ashrrev_i32_e32 v229, 31, v228
	v_lshl_add_u64 v[228:229], v[228:229], 2, s[42:43]
	global_load_dwordx2 v[200:201], v[228:229], off
	v_or_b32_e32 v228, s45, v175
	v_ashrrev_i32_e32 v229, 31, v228
	v_lshl_add_u64 v[228:229], v[228:229], 2, s[42:43]
	global_load_dwordx2 v[202:203], v[228:229], off
	v_or_b32_e32 v228, s45, v177
	v_ashrrev_i32_e32 v229, 31, v228
	v_lshl_add_u64 v[228:229], v[228:229], 2, s[42:43]
	global_load_dwordx2 v[204:205], v[228:229], off
	v_or_b32_e32 v228, s45, v179
	v_ashrrev_i32_e32 v229, 31, v228
	v_lshl_add_u64 v[228:229], v[228:229], 2, s[42:43]
	global_load_dwordx2 v[206:207], v[228:229], off
	v_or_b32_e32 v228, s45, v181
	v_ashrrev_i32_e32 v229, 31, v228
	v_lshl_add_u64 v[228:229], v[228:229], 2, s[42:43]
	global_load_dwordx2 v[208:209], v[228:229], off
	v_or_b32_e32 v228, s45, v183
	v_ashrrev_i32_e32 v229, 31, v228
	v_lshl_add_u64 v[228:229], v[228:229], 2, s[42:43]
	global_load_dwordx2 v[210:211], v[228:229], off
	v_or_b32_e32 v228, s45, v185
	v_ashrrev_i32_e32 v229, 31, v228
	v_lshl_add_u64 v[228:229], v[228:229], 2, s[42:43]
	global_load_dwordx2 v[212:213], v[228:229], off
	v_or_b32_e32 v228, s45, v187
	v_ashrrev_i32_e32 v229, 31, v228
	v_lshl_add_u64 v[228:229], v[228:229], 2, s[42:43]
	global_load_dwordx2 v[214:215], v[228:229], off
	v_or_b32_e32 v228, s45, v188
	v_ashrrev_i32_e32 v229, 31, v228
	v_lshl_add_u64 v[228:229], v[228:229], 2, s[42:43]
	global_load_dwordx2 v[216:217], v[228:229], off
	v_or_b32_e32 v228, s45, v189
	v_ashrrev_i32_e32 v229, 31, v228
	v_lshl_add_u64 v[228:229], v[228:229], 2, s[42:43]
	global_load_dwordx2 v[218:219], v[228:229], off
	v_or_b32_e32 v228, s45, v190
	v_ashrrev_i32_e32 v229, 31, v228
	v_lshl_add_u64 v[228:229], v[228:229], 2, s[42:43]
	global_load_dwordx2 v[230:231], v[228:229], off
.LBB0_99:
	s_waitcnt vmcnt(0)
	v_mul_f32_e32 v126, v126, v140
	v_bfe_u32 v132, v126, 17, 1
	v_mul_f32_e32 v122, v122, v141
	v_add3_u32 v126, v126, v132, s86
	v_bfe_u32 v132, v122, 17, 1
	v_add3_u32 v122, v122, v132, s86
	v_and_b32_e32 v126, 0xfffe0000, v126
	v_and_b32_e32 v122, 0xfffe0000, v122
	v_cvt_pk_bf16_f32 v126, v126, v122
	v_add_u32_e32 v122, v142, v143
	ds_write_b32 v122, v126
	v_mul_f32_e32 v126, v127, v140
	v_bfe_u32 v127, v126, 17, 1
	v_mul_f32_e32 v123, v123, v141
	v_add3_u32 v126, v126, v127, s86
	v_bfe_u32 v127, v123, 17, 1
	v_add3_u32 v123, v123, v127, s86
	v_and_b32_e32 v123, 0xfffe0000, v123
	v_and_b32_e32 v126, 0xfffe0000, v126
	v_cvt_pk_bf16_f32 v123, v126, v123
	ds_write_b32 v122, v123 offset:128
	v_mul_f32_e32 v123, v128, v140
	v_bfe_u32 v126, v123, 17, 1
	v_mul_f32_e32 v124, v124, v141
	v_add3_u32 v123, v123, v126, s86
	v_bfe_u32 v126, v124, 17, 1
	v_and_b32_e32 v123, 0xfffe0000, v123
	v_add3_u32 v124, v124, v126, s86
	v_and_b32_e32 v124, 0xfffe0000, v124
	v_cvt_pk_bf16_f32 v123, v123, v124
	ds_write_b32 v122, v123 offset:256
	v_mul_f32_e32 v123, v129, v140
	v_bfe_u32 v124, v123, 17, 1
	v_add3_u32 v123, v123, v124, s86
	v_mul_f32_e32 v124, v125, v141
	v_bfe_u32 v125, v124, 17, 1
	v_and_b32_e32 v123, 0xfffe0000, v123
	v_add3_u32 v124, v124, v125, s86
	s_and_b64 vcc, exec, s[4:5]
	v_mov_b32_e32 v139, 1.0
	v_and_b32_e32 v124, 0xfffe0000, v124
	v_cvt_pk_bf16_f32 v123, v123, v124
	ds_write_b32 v122, v123 offset:384
	s_cbranch_vccnz .LBB0_101
	v_mov_b32_e32 v138, v192
	v_mov_b32_e32 v139, v193
	s_nop 0
	s_nop 0
.LBB0_101:
	s_waitcnt vmcnt(0)
	v_mul_f32_e32 v118, v118, v138
	v_bfe_u32 v123, v118, 17, 1
	v_mul_f32_e32 v114, v114, v139
	v_add3_u32 v118, v118, v123, s86
	v_bfe_u32 v123, v114, 17, 1
	v_add3_u32 v114, v114, v123, s86
	v_and_b32_e32 v114, 0xfffe0000, v114
	v_and_b32_e32 v118, 0xfffe0000, v118
	v_cvt_pk_bf16_f32 v114, v118, v114
	ds_write_b32 v122, v114 offset:1032
	v_mul_f32_e32 v114, v119, v138
	v_bfe_u32 v118, v114, 17, 1
	v_mul_f32_e32 v115, v115, v139
	v_add3_u32 v114, v114, v118, s86
	v_bfe_u32 v118, v115, 17, 1
	v_and_b32_e32 v114, 0xfffe0000, v114
	v_add3_u32 v115, v115, v118, s86
	v_and_b32_e32 v115, 0xfffe0000, v115
	v_cvt_pk_bf16_f32 v114, v114, v115
	ds_write_b32 v122, v114 offset:1160
	v_mul_f32_e32 v114, v120, v138
	v_bfe_u32 v115, v114, 17, 1
	v_add3_u32 v114, v114, v115, s86
	v_mul_f32_e32 v115, v116, v139
	v_bfe_u32 v116, v115, 17, 1
	v_and_b32_e32 v114, 0xfffe0000, v114
	v_add3_u32 v115, v115, v116, s86
	v_and_b32_e32 v115, 0xfffe0000, v115
	v_cvt_pk_bf16_f32 v114, v114, v115
	ds_write_b32 v122, v114 offset:1288
	v_mul_f32_e32 v114, v121, v138
	v_bfe_u32 v115, v114, 17, 1
	v_add3_u32 v114, v114, v115, s86
	v_mul_f32_e32 v115, v117, v139
	v_bfe_u32 v116, v115, 17, 1
	v_and_b32_e32 v114, 0xfffe0000, v114
	v_add3_u32 v115, v115, v116, s86
	v_and_b32_e32 v115, 0xfffe0000, v115
	v_cvt_pk_bf16_f32 v114, v114, v115
	ds_write_b32 v122, v114 offset:1416
	v_mov_b32_e32 v114, 1.0
	s_and_b64 vcc, exec, s[4:5]
	v_mov_b32_e32 v116, 1.0
	v_mov_b32_e32 v117, 1.0
	s_cbranch_vccnz .LBB0_103
	v_mov_b32_e32 v116, v194
	v_mov_b32_e32 v117, v195
	s_nop 0
	s_nop 0
.LBB0_103:
	s_waitcnt vmcnt(0)
	v_mul_f32_e32 v110, v110, v116
	v_bfe_u32 v115, v110, 17, 1
	v_mul_f32_e32 v106, v106, v117
	v_add3_u32 v110, v110, v115, s86
	v_bfe_u32 v115, v106, 17, 1
	v_add3_u32 v106, v106, v115, s86
	v_and_b32_e32 v110, 0xfffe0000, v110
	v_and_b32_e32 v106, 0xfffe0000, v106
	v_cvt_pk_bf16_f32 v106, v110, v106
	v_add_u32_e32 v110, v142, v168
	ds_write_b32 v110, v106
	v_mul_f32_e32 v106, v111, v116
	v_bfe_u32 v111, v106, 17, 1
	v_mul_f32_e32 v107, v107, v117
	v_add3_u32 v106, v106, v111, s86
	v_bfe_u32 v111, v107, 17, 1
	v_and_b32_e32 v106, 0xfffe0000, v106
	v_add3_u32 v107, v107, v111, s86
	v_and_b32_e32 v107, 0xfffe0000, v107
	v_cvt_pk_bf16_f32 v106, v106, v107
	ds_write_b32 v110, v106 offset:128
	v_mul_f32_e32 v106, v112, v116
	v_bfe_u32 v107, v106, 17, 1
	v_add3_u32 v106, v106, v107, s86
	v_mul_f32_e32 v107, v108, v117
	v_bfe_u32 v108, v107, 17, 1
	v_and_b32_e32 v106, 0xfffe0000, v106
	v_add3_u32 v107, v107, v108, s86
	v_and_b32_e32 v107, 0xfffe0000, v107
	v_cvt_pk_bf16_f32 v106, v106, v107
	ds_write_b32 v110, v106 offset:256
	v_mul_f32_e32 v106, v113, v116
	v_bfe_u32 v107, v106, 17, 1
	v_add3_u32 v106, v106, v107, s86
	v_mul_f32_e32 v107, v109, v117
	v_bfe_u32 v108, v107, 17, 1
	v_and_b32_e32 v106, 0xfffe0000, v106
	v_add3_u32 v107, v107, v108, s86
	s_and_b64 vcc, exec, s[4:5]
	v_mov_b32_e32 v115, 1.0
	v_and_b32_e32 v107, 0xfffe0000, v107
	v_cvt_pk_bf16_f32 v106, v106, v107
	ds_write_b32 v110, v106 offset:384
	s_cbranch_vccnz .LBB0_105
	v_mov_b32_e32 v114, v196
	v_mov_b32_e32 v115, v197
	s_nop 0
	s_nop 0
.LBB0_105:
	s_waitcnt vmcnt(0)
	v_mul_f32_e32 v102, v102, v114
	v_bfe_u32 v106, v102, 17, 1
	v_mul_f32_e32 v98, v98, v115
	v_add3_u32 v102, v102, v106, s86
	v_bfe_u32 v106, v98, 17, 1
	v_add3_u32 v98, v98, v106, s86
	v_and_b32_e32 v102, 0xfffe0000, v102
	v_and_b32_e32 v98, 0xfffe0000, v98
	v_cvt_pk_bf16_f32 v98, v102, v98
	v_add_u32_e32 v102, v142, v170
	ds_write_b32 v102, v98
	v_mul_f32_e32 v98, v103, v114
	v_bfe_u32 v103, v98, 17, 1
	v_mul_f32_e32 v99, v99, v115
	v_add3_u32 v98, v98, v103, s86
	v_bfe_u32 v103, v99, 17, 1
	v_and_b32_e32 v98, 0xfffe0000, v98
	v_add3_u32 v99, v99, v103, s86
	v_and_b32_e32 v99, 0xfffe0000, v99
	v_cvt_pk_bf16_f32 v98, v98, v99
	ds_write_b32 v102, v98 offset:128
	v_mul_f32_e32 v98, v104, v114
	v_bfe_u32 v99, v98, 17, 1
	v_add3_u32 v98, v98, v99, s86
	v_mul_f32_e32 v99, v100, v115
	v_bfe_u32 v100, v99, 17, 1
	v_and_b32_e32 v98, 0xfffe0000, v98
	v_add3_u32 v99, v99, v100, s86
	v_and_b32_e32 v99, 0xfffe0000, v99
	v_cvt_pk_bf16_f32 v98, v98, v99
	ds_write_b32 v102, v98 offset:256
	v_mul_f32_e32 v98, v105, v114
	v_bfe_u32 v99, v98, 17, 1
	v_add3_u32 v98, v98, v99, s86
	v_mul_f32_e32 v99, v101, v115
	v_bfe_u32 v100, v99, 17, 1
	v_and_b32_e32 v98, 0xfffe0000, v98
	v_add3_u32 v99, v99, v100, s86
	v_and_b32_e32 v99, 0xfffe0000, v99
	v_cvt_pk_bf16_f32 v98, v98, v99
	ds_write_b32 v102, v98 offset:384
	v_mov_b32_e32 v98, 1.0
	s_and_b64 vcc, exec, s[4:5]
	v_mov_b32_e32 v100, 1.0
	v_mov_b32_e32 v101, 1.0
	s_cbranch_vccnz .LBB0_107
	v_mov_b32_e32 v100, v198
	v_mov_b32_e32 v101, v199
	s_nop 0
	s_nop 0
.LBB0_107:
	s_waitcnt vmcnt(0)
	v_mul_f32_e32 v94, v94, v100
	v_bfe_u32 v99, v94, 17, 1
	v_mul_f32_e32 v90, v90, v101
	v_add3_u32 v94, v94, v99, s86
	v_bfe_u32 v99, v90, 17, 1
	v_add3_u32 v90, v90, v99, s86
	v_and_b32_e32 v94, 0xfffe0000, v94
	v_and_b32_e32 v90, 0xfffe0000, v90
	v_cvt_pk_bf16_f32 v90, v94, v90
	v_add_u32_e32 v94, v142, v172
	ds_write_b32 v94, v90
	v_mul_f32_e32 v90, v95, v100
	v_bfe_u32 v95, v90, 17, 1
	v_mul_f32_e32 v91, v91, v101
	v_add3_u32 v90, v90, v95, s86
	v_bfe_u32 v95, v91, 17, 1
	v_and_b32_e32 v90, 0xfffe0000, v90
	v_add3_u32 v91, v91, v95, s86
	v_and_b32_e32 v91, 0xfffe0000, v91
	v_cvt_pk_bf16_f32 v90, v90, v91
	ds_write_b32 v94, v90 offset:128
	v_mul_f32_e32 v90, v96, v100
	v_bfe_u32 v91, v90, 17, 1
	v_add3_u32 v90, v90, v91, s86
	v_mul_f32_e32 v91, v92, v101
	v_bfe_u32 v92, v91, 17, 1
	v_and_b32_e32 v90, 0xfffe0000, v90
	v_add3_u32 v91, v91, v92, s86
	v_and_b32_e32 v91, 0xfffe0000, v91
	v_cvt_pk_bf16_f32 v90, v90, v91
	ds_write_b32 v94, v90 offset:256
	v_mul_f32_e32 v90, v97, v100
	v_bfe_u32 v91, v90, 17, 1
	v_add3_u32 v90, v90, v91, s86
	v_mul_f32_e32 v91, v93, v101
	v_bfe_u32 v92, v91, 17, 1
	v_and_b32_e32 v90, 0xfffe0000, v90
	v_add3_u32 v91, v91, v92, s86
	s_and_b64 vcc, exec, s[4:5]
	v_mov_b32_e32 v99, 1.0
	v_and_b32_e32 v91, 0xfffe0000, v91
	v_cvt_pk_bf16_f32 v90, v90, v91
	ds_write_b32 v94, v90 offset:384
	s_cbranch_vccnz .LBB0_109
	v_mov_b32_e32 v98, v200
	v_mov_b32_e32 v99, v201
	s_nop 0
	s_nop 0
.LBB0_109:
	s_waitcnt vmcnt(0)
	v_mul_f32_e32 v86, v86, v98
	v_bfe_u32 v90, v86, 17, 1
	v_mul_f32_e32 v82, v82, v99
	v_add3_u32 v86, v86, v90, s86
	v_bfe_u32 v90, v82, 17, 1
	v_add3_u32 v82, v82, v90, s86
	v_and_b32_e32 v86, 0xfffe0000, v86
	v_and_b32_e32 v82, 0xfffe0000, v82
	v_cvt_pk_bf16_f32 v82, v86, v82
	v_add_u32_e32 v86, v142, v174
	ds_write_b32 v86, v82
	v_mul_f32_e32 v82, v87, v98
	v_bfe_u32 v87, v82, 17, 1
	v_mul_f32_e32 v83, v83, v99
	v_add3_u32 v82, v82, v87, s86
	v_bfe_u32 v87, v83, 17, 1
	v_and_b32_e32 v82, 0xfffe0000, v82
	v_add3_u32 v83, v83, v87, s86
	v_and_b32_e32 v83, 0xfffe0000, v83
	v_cvt_pk_bf16_f32 v82, v82, v83
	ds_write_b32 v86, v82 offset:128
	v_mul_f32_e32 v82, v88, v98
	v_bfe_u32 v83, v82, 17, 1
	v_add3_u32 v82, v82, v83, s86
	v_mul_f32_e32 v83, v84, v99
	v_bfe_u32 v84, v83, 17, 1
	v_and_b32_e32 v82, 0xfffe0000, v82
	v_add3_u32 v83, v83, v84, s86
	v_and_b32_e32 v83, 0xfffe0000, v83
	v_cvt_pk_bf16_f32 v82, v82, v83
	ds_write_b32 v86, v82 offset:256
	v_mul_f32_e32 v82, v89, v98
	v_bfe_u32 v83, v82, 17, 1
	v_add3_u32 v82, v82, v83, s86
	v_mul_f32_e32 v83, v85, v99
	v_bfe_u32 v84, v83, 17, 1
	v_and_b32_e32 v82, 0xfffe0000, v82
	v_add3_u32 v83, v83, v84, s86
	v_and_b32_e32 v83, 0xfffe0000, v83
	v_cvt_pk_bf16_f32 v82, v82, v83
	ds_write_b32 v86, v82 offset:384
	v_mov_b32_e32 v82, 1.0
	s_and_b64 vcc, exec, s[4:5]
	v_mov_b32_e32 v84, 1.0
	v_mov_b32_e32 v85, 1.0
	s_cbranch_vccnz .LBB0_111
	v_mov_b32_e32 v84, v202
	v_mov_b32_e32 v85, v203
	s_nop 0
	s_nop 0
.LBB0_111:
	s_waitcnt vmcnt(0)
	v_mul_f32_e32 v78, v78, v84
	v_bfe_u32 v83, v78, 17, 1
	v_mul_f32_e32 v74, v74, v85
	v_add3_u32 v78, v78, v83, s86
	v_bfe_u32 v83, v74, 17, 1
	v_add3_u32 v74, v74, v83, s86
	v_and_b32_e32 v78, 0xfffe0000, v78
	v_and_b32_e32 v74, 0xfffe0000, v74
	v_cvt_pk_bf16_f32 v74, v78, v74
	v_add_u32_e32 v78, v142, v176
	ds_write_b32 v78, v74
	v_mul_f32_e32 v74, v79, v84
	v_bfe_u32 v79, v74, 17, 1
	v_mul_f32_e32 v75, v75, v85
	v_add3_u32 v74, v74, v79, s86
	v_bfe_u32 v79, v75, 17, 1
	v_and_b32_e32 v74, 0xfffe0000, v74
	v_add3_u32 v75, v75, v79, s86
	v_and_b32_e32 v75, 0xfffe0000, v75
	v_cvt_pk_bf16_f32 v74, v74, v75
	ds_write_b32 v78, v74 offset:128
	v_mul_f32_e32 v74, v80, v84
	v_bfe_u32 v75, v74, 17, 1
	v_add3_u32 v74, v74, v75, s86
	v_mul_f32_e32 v75, v76, v85
	v_bfe_u32 v76, v75, 17, 1
	v_and_b32_e32 v74, 0xfffe0000, v74
	v_add3_u32 v75, v75, v76, s86
	v_and_b32_e32 v75, 0xfffe0000, v75
	v_cvt_pk_bf16_f32 v74, v74, v75
	ds_write_b32 v78, v74 offset:256
	v_mul_f32_e32 v74, v81, v84
	v_bfe_u32 v75, v74, 17, 1
	v_add3_u32 v74, v74, v75, s86
	v_mul_f32_e32 v75, v77, v85
	v_bfe_u32 v76, v75, 17, 1
	v_and_b32_e32 v74, 0xfffe0000, v74
	v_add3_u32 v75, v75, v76, s86
	s_and_b64 vcc, exec, s[4:5]
	v_mov_b32_e32 v83, 1.0
	v_and_b32_e32 v75, 0xfffe0000, v75
	v_cvt_pk_bf16_f32 v74, v74, v75
	ds_write_b32 v78, v74 offset:384
	s_cbranch_vccnz .LBB0_113
	v_mov_b32_e32 v82, v204
	v_mov_b32_e32 v83, v205
	s_nop 0
	s_nop 0
.LBB0_113:
	s_waitcnt vmcnt(0)
	v_mul_f32_e32 v70, v70, v82
	v_bfe_u32 v74, v70, 17, 1
	v_mul_f32_e32 v66, v66, v83
	v_add3_u32 v70, v70, v74, s86
	v_bfe_u32 v74, v66, 17, 1
	v_add3_u32 v66, v66, v74, s86
	v_and_b32_e32 v70, 0xfffe0000, v70
	v_and_b32_e32 v66, 0xfffe0000, v66
	v_cvt_pk_bf16_f32 v66, v70, v66
	v_add_u32_e32 v70, v142, v178
	ds_write_b32 v70, v66
	v_mul_f32_e32 v66, v71, v82
	v_bfe_u32 v71, v66, 17, 1
	v_mul_f32_e32 v67, v67, v83
	v_add3_u32 v66, v66, v71, s86
	v_bfe_u32 v71, v67, 17, 1
	v_and_b32_e32 v66, 0xfffe0000, v66
	v_add3_u32 v67, v67, v71, s86
	v_and_b32_e32 v67, 0xfffe0000, v67
	v_cvt_pk_bf16_f32 v66, v66, v67
	ds_write_b32 v70, v66 offset:128
	v_mul_f32_e32 v66, v72, v82
	v_bfe_u32 v67, v66, 17, 1
	v_add3_u32 v66, v66, v67, s86
	v_mul_f32_e32 v67, v68, v83
	v_bfe_u32 v68, v67, 17, 1
	v_and_b32_e32 v66, 0xfffe0000, v66
	v_add3_u32 v67, v67, v68, s86
	v_and_b32_e32 v67, 0xfffe0000, v67
	v_cvt_pk_bf16_f32 v66, v66, v67
	ds_write_b32 v70, v66 offset:256
	v_mul_f32_e32 v66, v73, v82
	v_bfe_u32 v67, v66, 17, 1
	v_add3_u32 v66, v66, v67, s86
	v_mul_f32_e32 v67, v69, v83
	v_bfe_u32 v68, v67, 17, 1
	v_and_b32_e32 v66, 0xfffe0000, v66
	v_add3_u32 v67, v67, v68, s86
	v_and_b32_e32 v67, 0xfffe0000, v67
	v_cvt_pk_bf16_f32 v66, v66, v67
	ds_write_b32 v70, v66 offset:384
	v_mov_b32_e32 v66, 1.0
	s_and_b64 vcc, exec, s[4:5]
	v_mov_b32_e32 v68, 1.0
	v_mov_b32_e32 v69, 1.0
	s_cbranch_vccnz .LBB0_115
	v_mov_b32_e32 v68, v206
	v_mov_b32_e32 v69, v207
	s_nop 0
	s_nop 0
.LBB0_115:
	s_waitcnt vmcnt(0)
	v_mul_f32_e32 v62, v62, v68
	v_bfe_u32 v67, v62, 17, 1
	v_mul_f32_e32 v58, v58, v69
	v_add3_u32 v62, v62, v67, s86
	v_bfe_u32 v67, v58, 17, 1
	v_add3_u32 v58, v58, v67, s86
	v_and_b32_e32 v62, 0xfffe0000, v62
	v_and_b32_e32 v58, 0xfffe0000, v58
	v_cvt_pk_bf16_f32 v58, v62, v58
	v_add_u32_e32 v62, v142, v180
	ds_write_b32 v62, v58
	v_mul_f32_e32 v58, v63, v68
	v_bfe_u32 v63, v58, 17, 1
	v_mul_f32_e32 v59, v59, v69
	v_add3_u32 v58, v58, v63, s86
	v_bfe_u32 v63, v59, 17, 1
	v_and_b32_e32 v58, 0xfffe0000, v58
	v_add3_u32 v59, v59, v63, s86
	v_and_b32_e32 v59, 0xfffe0000, v59
	v_cvt_pk_bf16_f32 v58, v58, v59
	ds_write_b32 v62, v58 offset:128
	v_mul_f32_e32 v58, v64, v68
	v_bfe_u32 v59, v58, 17, 1
	v_add3_u32 v58, v58, v59, s86
	v_mul_f32_e32 v59, v60, v69
	v_bfe_u32 v60, v59, 17, 1
	v_and_b32_e32 v58, 0xfffe0000, v58
	v_add3_u32 v59, v59, v60, s86
	v_and_b32_e32 v59, 0xfffe0000, v59
	v_cvt_pk_bf16_f32 v58, v58, v59
	ds_write_b32 v62, v58 offset:256
	v_mul_f32_e32 v58, v65, v68
	v_bfe_u32 v59, v58, 17, 1
	v_add3_u32 v58, v58, v59, s86
	v_mul_f32_e32 v59, v61, v69
	v_bfe_u32 v60, v59, 17, 1
	v_and_b32_e32 v58, 0xfffe0000, v58
	v_add3_u32 v59, v59, v60, s86
	s_and_b64 vcc, exec, s[4:5]
	v_mov_b32_e32 v67, 1.0
	v_and_b32_e32 v59, 0xfffe0000, v59
	v_cvt_pk_bf16_f32 v58, v58, v59
	ds_write_b32 v62, v58 offset:384
	s_cbranch_vccnz .LBB0_117
	v_mov_b32_e32 v66, v208
	v_mov_b32_e32 v67, v209
	s_nop 0
	s_nop 0
.LBB0_117:
	s_waitcnt vmcnt(0)
	v_mul_f32_e32 v54, v54, v66
	v_bfe_u32 v58, v54, 17, 1
	v_mul_f32_e32 v50, v50, v67
	v_add3_u32 v54, v54, v58, s86
	v_bfe_u32 v58, v50, 17, 1
	v_add3_u32 v50, v50, v58, s86
	v_and_b32_e32 v54, 0xfffe0000, v54
	v_and_b32_e32 v50, 0xfffe0000, v50
	v_cvt_pk_bf16_f32 v50, v54, v50
	v_add_u32_e32 v54, v142, v182
	ds_write_b32 v54, v50
	v_mul_f32_e32 v50, v55, v66
	v_bfe_u32 v55, v50, 17, 1
	v_mul_f32_e32 v51, v51, v67
	v_add3_u32 v50, v50, v55, s86
	v_bfe_u32 v55, v51, 17, 1
	v_and_b32_e32 v50, 0xfffe0000, v50
	v_add3_u32 v51, v51, v55, s86
	v_and_b32_e32 v51, 0xfffe0000, v51
	v_cvt_pk_bf16_f32 v50, v50, v51
	ds_write_b32 v54, v50 offset:128
	v_mul_f32_e32 v50, v56, v66
	v_bfe_u32 v51, v50, 17, 1
	v_add3_u32 v50, v50, v51, s86
	v_mul_f32_e32 v51, v52, v67
	v_bfe_u32 v52, v51, 17, 1
	v_and_b32_e32 v50, 0xfffe0000, v50
	v_add3_u32 v51, v51, v52, s86
	v_and_b32_e32 v51, 0xfffe0000, v51
	v_cvt_pk_bf16_f32 v50, v50, v51
	ds_write_b32 v54, v50 offset:256
	v_mul_f32_e32 v50, v57, v66
	v_bfe_u32 v51, v50, 17, 1
	v_add3_u32 v50, v50, v51, s86
	v_mul_f32_e32 v51, v53, v67
	v_bfe_u32 v52, v51, 17, 1
	v_and_b32_e32 v50, 0xfffe0000, v50
	v_add3_u32 v51, v51, v52, s86
	v_and_b32_e32 v51, 0xfffe0000, v51
	v_cvt_pk_bf16_f32 v50, v50, v51
	ds_write_b32 v54, v50 offset:384
	v_mov_b32_e32 v50, 1.0
	s_and_b64 vcc, exec, s[4:5]
	v_mov_b32_e32 v52, 1.0
	v_mov_b32_e32 v53, 1.0
	s_cbranch_vccnz .LBB0_119
	v_mov_b32_e32 v52, v210
	v_mov_b32_e32 v53, v211
	s_nop 0
	s_nop 0
.LBB0_119:
	s_waitcnt vmcnt(0)
	v_mul_f32_e32 v46, v46, v52
	v_bfe_u32 v51, v46, 17, 1
	v_mul_f32_e32 v42, v42, v53
	v_add3_u32 v46, v46, v51, s86
	v_bfe_u32 v51, v42, 17, 1
	v_add3_u32 v42, v42, v51, s86
	v_and_b32_e32 v46, 0xfffe0000, v46
	v_and_b32_e32 v42, 0xfffe0000, v42
	v_cvt_pk_bf16_f32 v42, v46, v42
	v_add_u32_e32 v46, v142, v184
	ds_write_b32 v46, v42
	v_mul_f32_e32 v42, v47, v52
	v_bfe_u32 v47, v42, 17, 1
	v_mul_f32_e32 v43, v43, v53
	v_add3_u32 v42, v42, v47, s86
	v_bfe_u32 v47, v43, 17, 1
	v_and_b32_e32 v42, 0xfffe0000, v42
	v_add3_u32 v43, v43, v47, s86
	v_and_b32_e32 v43, 0xfffe0000, v43
	v_cvt_pk_bf16_f32 v42, v42, v43
	ds_write_b32 v46, v42 offset:128
	v_mul_f32_e32 v42, v48, v52
	v_bfe_u32 v43, v42, 17, 1
	v_add3_u32 v42, v42, v43, s86
	v_mul_f32_e32 v43, v44, v53
	v_bfe_u32 v44, v43, 17, 1
	v_and_b32_e32 v42, 0xfffe0000, v42
	v_add3_u32 v43, v43, v44, s86
	v_and_b32_e32 v43, 0xfffe0000, v43
	v_cvt_pk_bf16_f32 v42, v42, v43
	ds_write_b32 v46, v42 offset:256
	v_mul_f32_e32 v42, v49, v52
	v_bfe_u32 v43, v42, 17, 1
	v_add3_u32 v42, v42, v43, s86
	v_mul_f32_e32 v43, v45, v53
	v_bfe_u32 v44, v43, 17, 1
	v_and_b32_e32 v42, 0xfffe0000, v42
	v_add3_u32 v43, v43, v44, s86
	s_and_b64 vcc, exec, s[4:5]
	v_mov_b32_e32 v51, 1.0
	v_and_b32_e32 v43, 0xfffe0000, v43
	v_cvt_pk_bf16_f32 v42, v42, v43
	ds_write_b32 v46, v42 offset:384
	s_cbranch_vccnz .LBB0_121
	v_mov_b32_e32 v50, v212
	v_mov_b32_e32 v51, v213
	s_nop 0
	s_nop 0
.LBB0_121:
	s_waitcnt vmcnt(0)
	v_mul_f32_e32 v38, v38, v50
	v_bfe_u32 v42, v38, 17, 1
	v_mul_f32_e32 v34, v34, v51
	v_add3_u32 v38, v38, v42, s86
	v_bfe_u32 v42, v34, 17, 1
	v_add3_u32 v34, v34, v42, s86
	v_and_b32_e32 v38, 0xfffe0000, v38
	v_and_b32_e32 v34, 0xfffe0000, v34
	v_cvt_pk_bf16_f32 v34, v38, v34
	v_add_u32_e32 v38, v142, v186
	ds_write_b32 v38, v34
	v_mul_f32_e32 v34, v39, v50
	v_bfe_u32 v39, v34, 17, 1
	v_mul_f32_e32 v35, v35, v51
	v_add3_u32 v34, v34, v39, s86
	v_bfe_u32 v39, v35, 17, 1
	v_and_b32_e32 v34, 0xfffe0000, v34
	v_add3_u32 v35, v35, v39, s86
	v_and_b32_e32 v35, 0xfffe0000, v35
	v_cvt_pk_bf16_f32 v34, v34, v35
	ds_write_b32 v38, v34 offset:128
	v_mul_f32_e32 v34, v40, v50
	v_bfe_u32 v35, v34, 17, 1
	v_add3_u32 v34, v34, v35, s86
	v_mul_f32_e32 v35, v36, v51
	v_bfe_u32 v36, v35, 17, 1
	v_and_b32_e32 v34, 0xfffe0000, v34
	v_add3_u32 v35, v35, v36, s86
	v_and_b32_e32 v35, 0xfffe0000, v35
	v_cvt_pk_bf16_f32 v34, v34, v35
	ds_write_b32 v38, v34 offset:256
	v_mul_f32_e32 v34, v41, v50
	v_bfe_u32 v35, v34, 17, 1
	v_add3_u32 v34, v34, v35, s86
	v_mul_f32_e32 v35, v37, v51
	v_bfe_u32 v36, v35, 17, 1
	v_and_b32_e32 v34, 0xfffe0000, v34
	v_add3_u32 v35, v35, v36, s86
	v_and_b32_e32 v35, 0xfffe0000, v35
	v_cvt_pk_bf16_f32 v34, v34, v35
	ds_write_b32 v38, v34 offset:384
	v_mov_b32_e32 v34, 1.0
	s_and_b64 vcc, exec, s[4:5]
	v_mov_b32_e32 v36, 1.0
	v_mov_b32_e32 v37, 1.0
	s_cbranch_vccnz .LBB0_123
	v_mov_b32_e32 v36, v214
	v_mov_b32_e32 v37, v215
	s_nop 0
	s_nop 0
.LBB0_123:
	s_waitcnt vmcnt(0)
	v_mul_f32_e32 v30, v30, v36
	v_bfe_u32 v35, v30, 17, 1
	v_mul_f32_e32 v26, v26, v37
	v_add3_u32 v30, v30, v35, s86
	v_bfe_u32 v35, v26, 17, 1
	v_add3_u32 v26, v26, v35, s86
	v_and_b32_e32 v26, 0xfffe0000, v26
	v_and_b32_e32 v30, 0xfffe0000, v30
	v_cvt_pk_bf16_f32 v26, v30, v26
	ds_write_b32 v38, v26 offset:1032
	v_mul_f32_e32 v26, v31, v36
	v_bfe_u32 v30, v26, 17, 1
	v_mul_f32_e32 v27, v27, v37
	v_add3_u32 v26, v26, v30, s86
	v_bfe_u32 v30, v27, 17, 1
	v_and_b32_e32 v26, 0xfffe0000, v26
	v_add3_u32 v27, v27, v30, s86
	v_and_b32_e32 v27, 0xfffe0000, v27
	v_cvt_pk_bf16_f32 v26, v26, v27
	ds_write_b32 v38, v26 offset:1160
	v_mul_f32_e32 v26, v32, v36
	v_bfe_u32 v27, v26, 17, 1
	v_add3_u32 v26, v26, v27, s86
	v_mul_f32_e32 v27, v28, v37
	v_bfe_u32 v28, v27, 17, 1
	v_and_b32_e32 v26, 0xfffe0000, v26
	v_add3_u32 v27, v27, v28, s86
	v_and_b32_e32 v27, 0xfffe0000, v27
	v_cvt_pk_bf16_f32 v26, v26, v27
	ds_write_b32 v38, v26 offset:1288
	v_mul_f32_e32 v26, v33, v36
	v_bfe_u32 v27, v26, 17, 1
	v_add3_u32 v26, v26, v27, s86
	v_mul_f32_e32 v27, v29, v37
	v_bfe_u32 v28, v27, 17, 1
	v_and_b32_e32 v26, 0xfffe0000, v26
	v_add3_u32 v27, v27, v28, s86
	s_and_b64 vcc, exec, s[4:5]
	v_mov_b32_e32 v35, 1.0
	v_and_b32_e32 v27, 0xfffe0000, v27
	v_cvt_pk_bf16_f32 v26, v26, v27
	ds_write_b32 v38, v26 offset:1416
	s_cbranch_vccnz .LBB0_125
	v_mov_b32_e32 v34, v216
	v_mov_b32_e32 v35, v217
	s_nop 0
	s_nop 0
.LBB0_125:
	s_waitcnt vmcnt(0)
	v_mul_f32_e32 v22, v22, v34
	v_bfe_u32 v26, v22, 17, 1
	v_mul_f32_e32 v18, v18, v35
	v_add3_u32 v22, v22, v26, s86
	v_bfe_u32 v26, v18, 17, 1
	v_add3_u32 v18, v18, v26, s86
	v_and_b32_e32 v18, 0xfffe0000, v18
	v_and_b32_e32 v22, 0xfffe0000, v22
	v_cvt_pk_bf16_f32 v18, v22, v18
	ds_write_b32 v38, v18 offset:2064
	v_mul_f32_e32 v18, v23, v34
	v_bfe_u32 v22, v18, 17, 1
	v_mul_f32_e32 v19, v19, v35
	v_add3_u32 v18, v18, v22, s86
	v_bfe_u32 v22, v19, 17, 1
	v_and_b32_e32 v18, 0xfffe0000, v18
	v_add3_u32 v19, v19, v22, s86
	v_and_b32_e32 v19, 0xfffe0000, v19
	v_cvt_pk_bf16_f32 v18, v18, v19
	ds_write_b32 v38, v18 offset:2192
	v_mul_f32_e32 v18, v24, v34
	v_bfe_u32 v19, v18, 17, 1
	v_add3_u32 v18, v18, v19, s86
	v_mul_f32_e32 v19, v20, v35
	v_bfe_u32 v20, v19, 17, 1
	v_and_b32_e32 v18, 0xfffe0000, v18
	v_add3_u32 v19, v19, v20, s86
	v_and_b32_e32 v19, 0xfffe0000, v19
	v_cvt_pk_bf16_f32 v18, v18, v19
	ds_write_b32 v38, v18 offset:2320
	v_mul_f32_e32 v18, v25, v34
	v_bfe_u32 v19, v18, 17, 1
	v_add3_u32 v18, v18, v19, s86
	v_mul_f32_e32 v19, v21, v35
	v_bfe_u32 v20, v19, 17, 1
	v_and_b32_e32 v18, 0xfffe0000, v18
	v_add3_u32 v19, v19, v20, s86
	v_and_b32_e32 v19, 0xfffe0000, v19
	v_cvt_pk_bf16_f32 v18, v18, v19
	ds_write_b32 v38, v18 offset:2448
	v_mov_b32_e32 v18, 1.0
	s_and_b64 vcc, exec, s[4:5]
	v_mov_b32_e32 v20, 1.0
	v_mov_b32_e32 v21, 1.0
	s_cbranch_vccnz .LBB0_127
	v_mov_b32_e32 v20, v218
	v_mov_b32_e32 v21, v219
	s_nop 0
	s_nop 0
.LBB0_127:
	s_waitcnt vmcnt(0)
	v_mul_f32_e32 v14, v14, v20
	v_bfe_u32 v19, v14, 17, 1
	v_mul_f32_e32 v10, v10, v21
	v_add3_u32 v14, v14, v19, s86
	v_bfe_u32 v19, v10, 17, 1
	v_add3_u32 v10, v10, v19, s86
	v_and_b32_e32 v10, 0xfffe0000, v10
	v_and_b32_e32 v14, 0xfffe0000, v14
	v_cvt_pk_bf16_f32 v10, v14, v10
	ds_write_b32 v38, v10 offset:3096
	v_mul_f32_e32 v10, v15, v20
	v_bfe_u32 v14, v10, 17, 1
	v_mul_f32_e32 v11, v11, v21
	v_add3_u32 v10, v10, v14, s86
	v_bfe_u32 v14, v11, 17, 1
	v_and_b32_e32 v10, 0xfffe0000, v10
	v_add3_u32 v11, v11, v14, s86
	v_and_b32_e32 v11, 0xfffe0000, v11
	v_cvt_pk_bf16_f32 v10, v10, v11
	ds_write_b32 v38, v10 offset:3224
	v_mul_f32_e32 v10, v16, v20
	v_bfe_u32 v11, v10, 17, 1
	v_add3_u32 v10, v10, v11, s86
	v_mul_f32_e32 v11, v12, v21
	v_bfe_u32 v12, v11, 17, 1
	v_and_b32_e32 v10, 0xfffe0000, v10
	v_add3_u32 v11, v11, v12, s86
	v_and_b32_e32 v11, 0xfffe0000, v11
	v_cvt_pk_bf16_f32 v10, v10, v11
	ds_write_b32 v38, v10 offset:3352
	v_mul_f32_e32 v10, v17, v20
	v_bfe_u32 v11, v10, 17, 1
	v_add3_u32 v10, v10, v11, s86
	v_mul_f32_e32 v11, v13, v21
	v_bfe_u32 v12, v11, 17, 1
	v_and_b32_e32 v10, 0xfffe0000, v10
	v_add3_u32 v11, v11, v12, s86
	s_and_b64 vcc, exec, s[4:5]
	v_mov_b32_e32 v19, 1.0
	v_and_b32_e32 v11, 0xfffe0000, v11
	v_cvt_pk_bf16_f32 v10, v10, v11
	ds_write_b32 v38, v10 offset:3480
	s_cbranch_vccnz .LBB0_12
	v_mov_b32_e32 v18, v230
	v_mov_b32_e32 v19, v231
	s_nop 0
	s_nop 0
	s_branch .LBB0_12
.LBB0_129:
	v_readlane_b32 s4, v247, 6
	s_nop 0
	s_cmp_lg_u32 s4, 0
	s_cbranch_scc1 .Lwin_ret_stub
	v_readlane_b32 s4, v241, 2
	v_readlane_b32 s5, v241, 3

.LBB0_347:
	s_cmpk_eq_i32 s66, 0x100
	s_cbranch_scc0 .Lwin_all
	s_cmpk_lt_i32 s74, 0x80
	s_cbranch_scc1 .Lwin_skip
.Lwin_all:
	v_writelane_b32 v242, s0, 0
	s_nop 1
	v_writelane_b32 v242, s1, 1
	s_nop 1
	v_writelane_b32 v242, s2, 2
	s_nop 1
	v_writelane_b32 v242, s3, 3
	s_nop 1
	v_writelane_b32 v242, s4, 4
	s_nop 1
	v_writelane_b32 v242, s5, 5
	s_nop 1
	v_writelane_b32 v242, s6, 6
	s_nop 1
	v_writelane_b32 v242, s7, 7
	s_nop 1
	v_writelane_b32 v242, s8, 8
	s_nop 1
	v_writelane_b32 v242, s9, 9
	s_nop 1
	v_writelane_b32 v242, s10, 10
	s_nop 1
	v_writelane_b32 v242, s11, 11
	s_nop 1
	v_writelane_b32 v242, s12, 12
	s_nop 1
	v_writelane_b32 v242, s13, 13
	s_nop 1
	v_writelane_b32 v242, s14, 14
	s_nop 1
	v_writelane_b32 v242, s15, 15
	s_nop 1
	v_writelane_b32 v242, s16, 16
	s_nop 1
	v_writelane_b32 v242, s17, 17
	s_nop 1
	v_writelane_b32 v242, s18, 18
	s_nop 1
	v_writelane_b32 v242, s19, 19
	s_nop 1
	v_writelane_b32 v242, s20, 20
	s_nop 1
	v_writelane_b32 v242, s21, 21
	s_nop 1
	v_writelane_b32 v242, s22, 22
	s_nop 1
	v_writelane_b32 v242, s23, 23
	s_nop 1
	v_writelane_b32 v242, s24, 24
	s_nop 1
	v_writelane_b32 v242, s25, 25
	s_nop 1
	v_writelane_b32 v242, s26, 26
	s_nop 1
	v_writelane_b32 v242, s27, 27
	s_nop 1
	v_writelane_b32 v242, s28, 28
	s_nop 1
	v_writelane_b32 v242, s29, 29
	s_nop 1
	v_writelane_b32 v242, s30, 30
	s_nop 1
	v_writelane_b32 v242, s31, 31
	s_nop 1
	v_writelane_b32 v242, s32, 32
	s_nop 1
	v_writelane_b32 v242, s33, 33
	s_nop 1
	v_writelane_b32 v242, s34, 34
	s_nop 1
	v_writelane_b32 v242, s35, 35
	s_nop 1
	v_writelane_b32 v242, s36, 36
	s_nop 1
	v_writelane_b32 v242, s37, 37
	s_nop 1
	v_writelane_b32 v242, s38, 38
	s_nop 1
	v_writelane_b32 v242, s39, 39
	s_nop 1
	v_writelane_b32 v242, s40, 40
	s_nop 1
	v_writelane_b32 v242, s41, 41
	s_nop 1
	v_writelane_b32 v242, s42, 42
	s_nop 1
	v_writelane_b32 v242, s43, 43
	s_nop 1
	v_writelane_b32 v242, s44, 44
	s_nop 1
	v_writelane_b32 v242, s45, 45
	s_nop 1
	v_writelane_b32 v242, s46, 46
	s_nop 1
	v_writelane_b32 v242, s47, 47
	s_nop 1
	v_writelane_b32 v242, s48, 48
	s_nop 1
	v_writelane_b32 v242, s49, 49
	s_nop 1
	v_writelane_b32 v242, s50, 50
	s_nop 1
	v_writelane_b32 v242, s51, 51
	s_nop 1
	v_writelane_b32 v242, s52, 52
	s_nop 1
	v_writelane_b32 v242, s53, 53
	s_nop 1
	v_writelane_b32 v242, s54, 54
	s_nop 1
	v_writelane_b32 v242, s55, 55
	s_nop 1
	v_writelane_b32 v242, s56, 56
	s_nop 1
	v_writelane_b32 v242, s57, 57
	s_nop 1
	v_writelane_b32 v242, s58, 58
	s_nop 1
	v_writelane_b32 v242, s59, 59
	s_nop 1
	v_writelane_b32 v242, s60, 60
	s_nop 1
	v_writelane_b32 v242, s61, 61
	s_nop 1
	v_writelane_b32 v242, s62, 62
	s_nop 1
	v_writelane_b32 v242, s63, 63
	s_nop 1
	v_writelane_b32 v243, s64, 0
	s_nop 1
	v_writelane_b32 v243, s65, 1
	s_nop 1
	v_writelane_b32 v243, s66, 2
	s_nop 1
	v_writelane_b32 v243, s67, 3
	s_nop 1
	v_writelane_b32 v243, s68, 4
	s_nop 1
	v_writelane_b32 v243, s69, 5
	s_nop 1
	v_writelane_b32 v243, s70, 6
	s_nop 1
	v_writelane_b32 v243, s71, 7
	s_nop 1
	v_writelane_b32 v243, s72, 8
	s_nop 1
	v_writelane_b32 v243, s73, 9
	s_nop 1
	v_writelane_b32 v243, s74, 10
	s_nop 1
	v_writelane_b32 v243, s75, 11
	s_nop 1
	v_writelane_b32 v243, s76, 12
	s_nop 1
	v_writelane_b32 v243, s77, 13
	s_nop 1
	v_writelane_b32 v243, s78, 14
	s_nop 1
	v_writelane_b32 v243, s79, 15
	s_nop 1
	v_writelane_b32 v243, s80, 16
	s_nop 1
	v_writelane_b32 v243, s81, 17
	s_nop 1
	v_writelane_b32 v243, s82, 18
	s_nop 1
	v_writelane_b32 v243, s83, 19
	s_nop 1
	v_writelane_b32 v243, s84, 20
	s_nop 1
	v_writelane_b32 v243, s85, 21
	s_nop 1
	v_writelane_b32 v243, s86, 22
	s_nop 1
	v_writelane_b32 v243, s87, 23
	s_nop 1
	v_writelane_b32 v243, s88, 24
	s_nop 1
	v_writelane_b32 v243, s89, 25
	s_nop 1
	v_writelane_b32 v243, s90, 26
	s_nop 1
	v_writelane_b32 v243, s91, 27
	s_nop 1
	v_writelane_b32 v243, s92, 28
	s_nop 1
	v_writelane_b32 v243, s93, 29
	s_nop 1
	v_writelane_b32 v243, s94, 30
	s_nop 1
	v_writelane_b32 v243, s95, 31
	s_nop 1
	v_writelane_b32 v243, s96, 32
	s_nop 1
	v_writelane_b32 v243, s97, 33
	s_nop 1
	v_writelane_b32 v243, s98, 34
	s_nop 1
	v_writelane_b32 v243, s99, 35
	s_nop 1
	v_writelane_b32 v243, vcc_lo, 36
	s_nop 1
	v_writelane_b32 v243, vcc_hi, 37
	s_mov_b64 s[0:1], exec
	s_nop 1
	v_writelane_b32 v243, s0, 38
	s_nop 1
	v_writelane_b32 v243, s1, 39
	s_mov_b64 exec, -1
	v_mov_b32_e32 v244, v241
	v_mov_b32_e32 v245, v4
	v_mov_b32_e32 v246, v33
	s_cmp_gt_u32 s70, 2
	s_cselect_b32 s4, 1, 0
	s_nop 0
	v_writelane_b32 v247, s4, 3
	s_movk_i32 s4, 0x1280
	s_nop 0
	v_writelane_b32 v247, s4, 0
	s_nop 1
	v_writelane_b32 v247, s4, 5
	s_movk_i32 s4, 0xb00
	s_nop 0
	v_writelane_b32 v247, s4, 1
	s_movk_i32 s4, 0x1400
	s_nop 0
	v_writelane_b32 v247, s4, 2
	s_lshl_b32 s4, s66, 3
	s_cmpk_eq_i32 s66, 0x100
	s_cselect_b32 s4, 0x400, s4
	s_cselect_b32 s3, 0x400, 0
	s_nop 0
	v_writelane_b32 v247, s4, 4
	s_mov_b32 s4, 1
	s_nop 0
	v_writelane_b32 v247, s4, 6
	s_load_dwordx8 s[8:15], s[30:31], 0x0
	s_load_dwordx4 s[24:27], s[30:31], 0x20
	s_load_dwordx2 s[6:7], s[30:31], 0x30
	s_load_dwordx4 s[64:67], s[30:31], 0xb0
	v_readfirstlane_b32 s2, v156
	s_lshl_b32 s4, s74, 3
	s_lshr_b32 s100, s2, 6
	s_add_i32 s100, s100, s4
	s_sub_i32 s100, s100, s3
	s_waitcnt lgkmcnt(0)
	s_branch .Lconv_pre
.Lwin_ret_stub:
	s_mov_b64 exec, -1
	s_waitcnt vmcnt(0) lgkmcnt(0)
	v_mov_b32_e32 v241, v244
	v_mov_b32_e32 v4, v245
	v_mov_b32_e32 v33, v246
	v_mov_b32_e32 v2, 0
	v_lshlrev_b32_e32 v158, 2, v157
	v_mov_b32_e32 v159, 0x3727c5ac
	v_mov_b64_e32 v[160:161], 0xb00
	v_mov_b64_e32 v[162:163], 0xaff
	v_mov_b64_e32 v[164:165], 0x380
	v_mov_b64_e32 v[166:167], 0x37f
	v_mov_b64_e32 v[168:169], 0x200
	v_mov_b64_e32 v[170:171], 0x1ff
	v_readlane_b32 s0, v243, 38
	v_readlane_b32 s1, v243, 39
	s_nop 1
	s_mov_b64 exec, s[0:1]
	v_readlane_b32 vcc_lo, v243, 36
	v_readlane_b32 vcc_hi, v243, 37
	v_readlane_b32 s0, v242, 0
	v_readlane_b32 s1, v242, 1
	v_readlane_b32 s2, v242, 2
	v_readlane_b32 s3, v242, 3
	v_readlane_b32 s4, v242, 4
	v_readlane_b32 s5, v242, 5
	v_readlane_b32 s6, v242, 6
	v_readlane_b32 s7, v242, 7
	v_readlane_b32 s8, v242, 8
	v_readlane_b32 s9, v242, 9
	v_readlane_b32 s10, v242, 10
	v_readlane_b32 s11, v242, 11
	v_readlane_b32 s12, v242, 12
	v_readlane_b32 s13, v242, 13
	v_readlane_b32 s14, v242, 14
	v_readlane_b32 s15, v242, 15
	v_readlane_b32 s16, v242, 16
	v_readlane_b32 s17, v242, 17
	v_readlane_b32 s18, v242, 18
	v_readlane_b32 s19, v242, 19
	v_readlane_b32 s20, v242, 20
	v_readlane_b32 s21, v242, 21
	v_readlane_b32 s22, v242, 22
	v_readlane_b32 s23, v242, 23
	v_readlane_b32 s24, v242, 24
	v_readlane_b32 s25, v242, 25
	v_readlane_b32 s26, v242, 26
	v_readlane_b32 s27, v242, 27
	v_readlane_b32 s28, v242, 28
	v_readlane_b32 s29, v242, 29
	v_readlane_b32 s30, v242, 30
	v_readlane_b32 s31, v242, 31
	v_readlane_b32 s32, v242, 32
	v_readlane_b32 s33, v242, 33
	v_readlane_b32 s34, v242, 34
	v_readlane_b32 s35, v242, 35
	v_readlane_b32 s36, v242, 36
	v_readlane_b32 s37, v242, 37
	v_readlane_b32 s38, v242, 38
	v_readlane_b32 s39, v242, 39
	v_readlane_b32 s40, v242, 40
	v_readlane_b32 s41, v242, 41
	v_readlane_b32 s42, v242, 42
	v_readlane_b32 s43, v242, 43
	v_readlane_b32 s44, v242, 44
	v_readlane_b32 s45, v242, 45
	v_readlane_b32 s46, v242, 46
	v_readlane_b32 s47, v242, 47
	v_readlane_b32 s48, v242, 48
	v_readlane_b32 s49, v242, 49
	v_readlane_b32 s50, v242, 50
	v_readlane_b32 s51, v242, 51
	v_readlane_b32 s52, v242, 52
	v_readlane_b32 s53, v242, 53
	v_readlane_b32 s54, v242, 54
	v_readlane_b32 s55, v242, 55
	v_readlane_b32 s56, v242, 56
	v_readlane_b32 s57, v242, 57
	v_readlane_b32 s58, v242, 58
	v_readlane_b32 s59, v242, 59
	v_readlane_b32 s60, v242, 60
	v_readlane_b32 s61, v242, 61
	v_readlane_b32 s62, v242, 62
	v_readlane_b32 s63, v242, 63
	v_readlane_b32 s64, v243, 0
	v_readlane_b32 s65, v243, 1
	v_readlane_b32 s66, v243, 2
	v_readlane_b32 s67, v243, 3
	v_readlane_b32 s68, v243, 4
	v_readlane_b32 s69, v243, 5
	v_readlane_b32 s70, v243, 6
	v_readlane_b32 s71, v243, 7
	v_readlane_b32 s72, v243, 8
	v_readlane_b32 s73, v243, 9
	v_readlane_b32 s74, v243, 10
	v_readlane_b32 s75, v243, 11
	v_readlane_b32 s76, v243, 12
	v_readlane_b32 s77, v243, 13
	v_readlane_b32 s78, v243, 14
	v_readlane_b32 s79, v243, 15
	v_readlane_b32 s80, v243, 16
	v_readlane_b32 s81, v243, 17
	v_readlane_b32 s82, v243, 18
	v_readlane_b32 s83, v243, 19
	v_readlane_b32 s84, v243, 20
	v_readlane_b32 s85, v243, 21
	v_readlane_b32 s86, v243, 22
	v_readlane_b32 s87, v243, 23
	v_readlane_b32 s88, v243, 24
	v_readlane_b32 s89, v243, 25
	v_readlane_b32 s90, v243, 26
	v_readlane_b32 s91, v243, 27
	v_readlane_b32 s92, v243, 28
	v_readlane_b32 s93, v243, 29
	v_readlane_b32 s94, v243, 30
	v_readlane_b32 s95, v243, 31
	v_readlane_b32 s96, v243, 32
	v_readlane_b32 s97, v243, 33
	v_readlane_b32 s98, v243, 34
	v_readlane_b32 s99, v243, 35
	s_nop 4

	.amdhsa_kernel _Z14fwd_megakernel4Args
		.amdhsa_group_segment_fixed_size 0
		.amdhsa_private_segment_fixed_size 0
		.amdhsa_kernarg_size 440
		.amdhsa_user_sgpr_count 2
		.amdhsa_user_sgpr_dispatch_ptr 0
		.amdhsa_user_sgpr_queue_ptr 0
		.amdhsa_user_sgpr_kernarg_segment_ptr 1
		.amdhsa_user_sgpr_dispatch_id 0
		.amdhsa_user_sgpr_kernarg_preload_length 0
		.amdhsa_user_sgpr_kernarg_preload_offset 0
		.amdhsa_user_sgpr_private_segment_size 0
		.amdhsa_uses_dynamic_stack 0
		.amdhsa_enable_private_segment 0
		.amdhsa_system_sgpr_workgroup_id_x 1
		.amdhsa_system_sgpr_workgroup_id_y 0
		.amdhsa_system_sgpr_workgroup_id_z 0
		.amdhsa_system_sgpr_workgroup_info 0
		.amdhsa_system_vgpr_workitem_id 2
		.amdhsa_next_free_vgpr 256
		.amdhsa_next_free_sgpr 102
		.amdhsa_accum_offset 256
		.amdhsa_reserve_vcc 1
		.amdhsa_float_round_mode_32 0
		.amdhsa_float_round_mode_16_64 0
		.amdhsa_float_denorm_mode_32 3
		.amdhsa_float_denorm_mode_16_64 3
		.amdhsa_dx10_clamp 1
		.amdhsa_ieee_mode 1
		.amdhsa_fp16_overflow 0
		.amdhsa_tg_split 0
		.amdhsa_exception_fp_ieee_invalid_op 0
		.amdhsa_exception_fp_denorm_src 0
		.amdhsa_exception_fp_ieee_div_zero 0
		.amdhsa_exception_fp_ieee_overflow 0
		.amdhsa_exception_fp_ieee_underflow 0
		.amdhsa_exception_fp_ieee_inexact 0
		.amdhsa_exception_int_div_zero 0
	.end_amdhsa_kernel

amdhsa.kernels:
  - .agpr_count:     0
    .args:
      - .offset:         0
        .size:           184
        .value_kind:     by_value
      - .offset:         184
        .size:           4
        .value_kind:     hidden_block_count_x
      - .offset:         188
        .size:           4
        .value_kind:     hidden_block_count_y
      - .offset:         192
        .size:           4
        .value_kind:     hidden_block_count_z
      - .offset:         196
        .size:           2
        .value_kind:     hidden_group_size_x
      - .offset:         198
        .size:           2
        .value_kind:     hidden_group_size_y
      - .offset:         200
        .size:           2
        .value_kind:     hidden_group_size_z
      - .offset:         202
        .size:           2
        .value_kind:     hidden_remainder_x
      - .offset:         204
        .size:           2
        .value_kind:     hidden_remainder_y
      - .offset:         206
        .size:           2
        .value_kind:     hidden_remainder_z
      - .offset:         224
        .size:           8
        .value_kind:     hidden_global_offset_x
      - .offset:         232
        .size:           8
        .value_kind:     hidden_global_offset_y
      - .offset:         240
        .size:           8
        .value_kind:     hidden_global_offset_z
      - .offset:         248
        .size:           2
        .value_kind:     hidden_grid_dims
      - .offset:         272
        .size:           8
        .value_kind:     hidden_multigrid_sync_arg
      - .offset:         304
        .size:           4
        .value_kind:     hidden_dynamic_lds_size
    .group_segment_fixed_size: 0
    .kernarg_segment_align: 8
    .kernarg_segment_size: 440
    .language:       OpenCL C
    .language_version:
      - 2
      - 0
    .max_flat_workgroup_size: 512
    .name:           _Z14fwd_megakernel4Args
    .private_segment_fixed_size: 0
    .sgpr_count:     108
    .sgpr_spill_count: 84
    .symbol:         _Z14fwd_megakernel4Args.kd
    .uniform_work_group_size: 1
    .uses_dynamic_stack: false
    .vgpr_count:     256
    .vgpr_spill_count: 0
    .wavefront_size: 64
